# nt cache hint on once-read loads (P0 x/weight reads, EpiResid base reads)
# speedup vs baseline: 1.0044x; 1.0044x over previous
; __device__ __forceinline__ void cvt_load(const CvtJob& J, f32x4 (&cv)[8], int wave, int lane) {
;     const int nblk = (J.N + 255) / 256, kb = J.item / nblk, nb = J.item % nblk, k0 = 64 * kb, n0 = 256 * nb;
;     const bool nok = (n0 + 4 * lane) < J.N;
; #pragma unroll
;     for (int i = 0; i < 8; ++i) { const int k = k0 + wave + 8 * i;
;         cv[i] = nok ? *(const f32x4*)(J.W + (size_t)k * J.N + n0 + 4 * lane) : (f32x4){0.f, 0.f, 0.f, 0.f};
;         if (J.gam) cv[i] = cv[i] * J.gam[k]; }
; }
; __global__ void __launch_bounds__(512, 2) mega_fwd(Args args) {
;     ...
;             CVT_DECODE_P0(cur, it); if (cur.ok) cvt_load(cur, cv, wave, lane);
.LBB0_39:
	v_cndmask_b32_e64 v0, 0, 1, s[4:5]
	v_cmp_ne_u32_e64 s[2:3], 1, v0
	s_andn2_b64 vcc, exec, s[4:5]
	s_cbranch_vccnz .LBB0_72
	s_add_i32 s4, s76, 0xff
	s_lshr_b32 s4, s4, 8
	s_abs_i32 s5, s4
	v_cvt_f32_u32_e32 v0, s5
	s_sub_i32 s33, 0, s5
	s_abs_i32 s6, s14
	s_xor_b32 s7, s14, s4
	v_rcp_iflag_f32_e32 v0, v0
	s_ashr_i32 s7, s7, 31
	v_lshlrev_b32_e32 v4, 2, v184
	v_lshlrev_b32_e32 v16, 2, v4
	v_mul_f32_e32 v0, 0x4f7ffffe, v0
	v_cvt_u32_f32_e32 v0, v0
	s_nop 0
	v_readfirstlane_b32 s34, v0
	s_mul_i32 s33, s33, s34
	s_mul_hi_u32 s33, s34, s33
	s_add_i32 s34, s34, s33
	s_mul_hi_u32 s33, s6, s34
	s_mul_i32 s34, s33, s5
	s_sub_i32 s6, s6, s34
	s_add_i32 s35, s33, 1
	s_sub_i32 s34, s6, s5
	s_cmp_ge_u32 s6, s5
	s_cselect_b32 s33, s35, s33
	s_cselect_b32 s6, s34, s6
	s_add_i32 s34, s33, 1
	s_cmp_ge_u32 s6, s5
	s_cselect_b32 s5, s34, s33
	s_xor_b32 s5, s5, s7
	s_sub_i32 s5, s5, s7
	s_mul_i32 s4, s5, s4
	s_sub_i32 s4, s14, s4
	s_lshl_b32 s70, s4, 8
	s_lshl_b32 s5, s5, 6
	v_readlane_b32 s6, v238, 37
	v_or_b32_e32 v0, s70, v4
	s_add_i32 s68, s5, s6
	v_cmp_gt_i32_e64 s[4:5], s76, v0
	v_mov_b32_e32 v0, 0
	s_ashr_i32 s71, s70, 31
	v_mov_b32_e32 v1, v0
	v_mov_b32_e32 v2, v0
	v_mov_b32_e32 v3, v0
	v_mov_b32_e32 v70, 1.0
	v_mov_b32_e32 v72, 1.0
	v_mov_b32_e32 v74, 1.0
	v_mov_b32_e32 v76, 1.0
	v_mov_b32_e32 v78, 1.0
	v_mov_b32_e32 v80, 1.0
	v_mov_b32_e32 v82, 1.0
	v_mov_b32_e32 v84, 1.0
	s_and_saveexec_b64 s[6:7], s[4:5]
	s_cbranch_execz .LBB0_42
	s_mul_hi_i32 s35, s68, s76
	s_mul_i32 s34, s68, s76
	s_lshl_b64 s[34:35], s[34:35], 2
	s_add_u32 s33, s0, s34
	s_addc_u32 s69, s1, s35
	s_lshl_b64 s[34:35], s[70:71], 2
	s_add_u32 s34, s33, s34
	s_addc_u32 s35, s69, s35
	global_load_dwordx4 v[0:3], v16, s[34:35] nt
.LBB0_42:
	s_or_b64 exec, exec, s[6:7]
	s_cmp_lg_u64 s[8:9], 0
	s_cselect_b64 s[72:73], -1, 0
	s_cmp_eq_u64 s[8:9], 0
	s_cbranch_scc1 .LBB0_44
	s_ashr_i32 s69, s68, 31
	s_lshl_b64 s[6:7], s[68:69], 2
	s_add_u32 s6, s8, s6
	s_addc_u32 s7, s9, s7
	v_mov_b32_e32 v4, 0
	global_load_dword v70, v4, s[6:7] nt
	s_nop 0
	s_nop 0
	s_nop 0
.LBB0_44:
	v_mov_b32_e32 v4, 0
	v_mov_b32_e32 v5, v4
	v_mov_b32_e32 v6, v4
	v_mov_b32_e32 v7, v4
	s_and_saveexec_b64 s[6:7], s[4:5]
	s_cbranch_execz .LBB0_46
	s_add_i32 s33, s68, 8
	s_mul_hi_i32 s35, s33, s76
	s_mul_i32 s34, s33, s76
	s_lshl_b64 s[34:35], s[34:35], 2
	s_add_u32 s33, s0, s34
	s_addc_u32 s69, s1, s35
	s_lshl_b64 s[34:35], s[70:71], 2
	s_add_u32 s34, s33, s34
	s_addc_u32 s35, s69, s35
	global_load_dwordx4 v[4:7], v16, s[34:35] nt
.LBB0_46:
	s_or_b64 exec, exec, s[6:7]
	v_cndmask_b32_e64 v8, 0, 1, s[72:73]
	v_cmp_ne_u32_e64 s[6:7], 1, v8
	s_andn2_b64 vcc, exec, s[72:73]
	s_cbranch_vccnz .LBB0_48
	s_ashr_i32 s69, s68, 31
	s_lshl_b64 s[34:35], s[68:69], 2
	s_add_u32 s34, s8, s34
	s_addc_u32 s35, s9, s35
	v_mov_b32_e32 v8, 0
	global_load_dword v72, v8, s[34:35] offset:32 nt
	s_nop 0
	s_nop 0
	s_nop 0
.LBB0_48:
	v_mov_b32_e32 v8, 0
	v_mov_b32_e32 v9, v8
	v_mov_b32_e32 v10, v8
	v_mov_b32_e32 v11, v8
	s_and_saveexec_b64 s[72:73], s[4:5]
	s_cbranch_execz .LBB0_50
	s_add_i32 s33, s68, 16
	s_mul_hi_i32 s35, s33, s76
	s_mul_i32 s34, s33, s76
	s_lshl_b64 s[34:35], s[34:35], 2
	s_add_u32 s33, s0, s34
	s_addc_u32 s69, s1, s35
	s_lshl_b64 s[34:35], s[70:71], 2
	s_add_u32 s34, s33, s34
	s_addc_u32 s35, s69, s35
	global_load_dwordx4 v[8:11], v16, s[34:35] nt
.LBB0_50:
	s_or_b64 exec, exec, s[72:73]
	s_and_b64 vcc, exec, s[6:7]
	s_cbranch_vccnz .LBB0_52
	s_ashr_i32 s69, s68, 31
	s_lshl_b64 s[34:35], s[68:69], 2
	s_add_u32 s34, s8, s34
	s_addc_u32 s35, s9, s35
	v_mov_b32_e32 v12, 0
	global_load_dword v74, v12, s[34:35] offset:64 nt
	s_nop 0
	s_nop 0
	s_nop 0
; __device__ __forceinline__ void cvt_load(const CvtJob& J, f32x4 (&cv)[8], int wave, int lane) {
;     ...
;     for (int i = 0; i < 8; ++i) { const int k = k0 + wave + 8 * i;
;         cv[i] = nok ? *(const f32x4*)(J.W + (size_t)k * J.N + n0 + 4 * lane) : (f32x4){0.f, 0.f, 0.f, 0.f};
;         if (J.gam) cv[i] = cv[i] * J.gam[k]; }
.LBB0_52:
	v_mov_b32_e32 v12, 0
	v_mov_b32_e32 v13, v12
	v_mov_b32_e32 v14, v12
	v_mov_b32_e32 v15, v12
	s_and_saveexec_b64 s[72:73], s[4:5]
	s_cbranch_execz .LBB0_54
	s_add_i32 s33, s68, 24
	s_mul_hi_i32 s35, s33, s76
	s_mul_i32 s34, s33, s76
	s_lshl_b64 s[34:35], s[34:35], 2
	s_add_u32 s33, s0, s34
	s_addc_u32 s69, s1, s35
	s_lshl_b64 s[34:35], s[70:71], 2
	s_add_u32 s34, s33, s34
	s_addc_u32 s35, s69, s35
	global_load_dwordx4 v[12:15], v16, s[34:35] nt
.LBB0_54:
	s_or_b64 exec, exec, s[72:73]
	s_and_b64 vcc, exec, s[6:7]
	s_cbranch_vccnz .LBB0_56
	s_ashr_i32 s69, s68, 31
	s_lshl_b64 s[34:35], s[68:69], 2
	s_add_u32 s34, s8, s34
	s_addc_u32 s35, s9, s35
	v_mov_b32_e32 v17, 0
	global_load_dword v76, v17, s[34:35] offset:96 nt
	s_nop 0
	s_nop 0
	s_nop 0
.LBB0_56:
	v_mov_b32_e32 v20, 0
	v_mov_b32_e32 v21, v20
	v_mov_b32_e32 v22, v20
	v_mov_b32_e32 v23, v20
	s_and_saveexec_b64 s[72:73], s[4:5]
	s_cbranch_execz .LBB0_58
	s_add_i32 s33, s68, 32
	s_mul_hi_i32 s35, s33, s76
	s_mul_i32 s34, s33, s76
	s_lshl_b64 s[34:35], s[34:35], 2
	s_add_u32 s33, s0, s34
	s_addc_u32 s69, s1, s35
	s_lshl_b64 s[34:35], s[70:71], 2
	s_add_u32 s34, s33, s34
	s_addc_u32 s35, s69, s35
	global_load_dwordx4 v[20:23], v16, s[34:35] nt
.LBB0_58:
	s_or_b64 exec, exec, s[72:73]
	s_and_b64 vcc, exec, s[6:7]
	s_cbranch_vccnz .LBB0_60
	s_ashr_i32 s69, s68, 31
	s_lshl_b64 s[34:35], s[68:69], 2
	s_add_u32 s34, s8, s34
	s_addc_u32 s35, s9, s35
	v_mov_b32_e32 v17, 0
	global_load_dword v78, v17, s[34:35] offset:128 nt
	s_nop 0
	s_nop 0
	s_nop 0
.LBB0_60:
	v_mov_b32_e32 v24, 0
	v_mov_b32_e32 v25, v24
	v_mov_b32_e32 v26, v24
	v_mov_b32_e32 v27, v24
	s_and_saveexec_b64 s[72:73], s[4:5]
	s_cbranch_execz .LBB0_62
	s_add_i32 s33, s68, 40
	s_mul_hi_i32 s35, s33, s76
	s_mul_i32 s34, s33, s76
	s_lshl_b64 s[34:35], s[34:35], 2
	s_add_u32 s33, s0, s34
	s_addc_u32 s69, s1, s35
	s_lshl_b64 s[34:35], s[70:71], 2
	s_add_u32 s34, s33, s34
	s_addc_u32 s35, s69, s35
	global_load_dwordx4 v[24:27], v16, s[34:35] nt
.LBB0_62:
	s_or_b64 exec, exec, s[72:73]
	s_and_b64 vcc, exec, s[6:7]
	s_cbranch_vccnz .LBB0_64
	s_ashr_i32 s69, s68, 31
	s_lshl_b64 s[34:35], s[68:69], 2
	s_add_u32 s34, s8, s34
	s_addc_u32 s35, s9, s35
	v_mov_b32_e32 v17, 0
	global_load_dword v80, v17, s[34:35] offset:160 nt
	s_nop 0
	s_nop 0
	s_nop 0
.LBB0_64:
	v_mov_b32_e32 v28, 0
	v_mov_b32_e32 v29, v28
	v_mov_b32_e32 v30, v28
	v_mov_b32_e32 v31, v28
	s_and_saveexec_b64 s[72:73], s[4:5]
	s_cbranch_execz .LBB0_66
	s_add_i32 s33, s68, 48
	s_mul_hi_i32 s35, s33, s76
	s_mul_i32 s34, s33, s76
	s_lshl_b64 s[34:35], s[34:35], 2
	s_add_u32 s33, s0, s34
	s_addc_u32 s69, s1, s35
	s_lshl_b64 s[34:35], s[70:71], 2
	s_add_u32 s34, s33, s34
	s_addc_u32 s35, s69, s35
	global_load_dwordx4 v[28:31], v16, s[34:35] nt
.LBB0_66:
	s_or_b64 exec, exec, s[72:73]
	s_and_b64 vcc, exec, s[6:7]
	s_cbranch_vccnz .LBB0_68
	s_ashr_i32 s69, s68, 31
	s_lshl_b64 s[34:35], s[68:69], 2
	s_add_u32 s34, s8, s34
	s_addc_u32 s35, s9, s35
	v_mov_b32_e32 v17, 0
	global_load_dword v82, v17, s[34:35] offset:192 nt
	s_nop 0
	s_nop 0
	s_nop 0
.LBB0_68:
	v_mov_b32_e32 v32, 0
	v_mov_b32_e32 v33, v32
	v_mov_b32_e32 v34, v32
	v_mov_b32_e32 v35, v32
	s_and_saveexec_b64 s[72:73], s[4:5]
	s_cbranch_execz .LBB0_70
	s_add_i32 s4, s68, 56
	s_mul_hi_i32 s5, s4, s76
	s_mul_i32 s4, s4, s76
	s_lshl_b64 s[4:5], s[4:5], 2
	s_add_u32 s4, s0, s4
	s_addc_u32 s5, s1, s5
	s_lshl_b64 s[0:1], s[70:71], 2
	s_add_u32 s0, s4, s0
	s_addc_u32 s1, s5, s1
	global_load_dwordx4 v[32:35], v16, s[0:1] nt
.LBB0_70:
	s_or_b64 exec, exec, s[72:73]
	s_and_b64 vcc, exec, s[6:7]
	s_cbranch_vccnz .LBB0_72
	s_ashr_i32 s69, s68, 31
	s_lshl_b64 s[0:1], s[68:69], 2
	s_add_u32 s0, s8, s0
	s_addc_u32 s1, s9, s1
	v_mov_b32_e32 v16, 0
	global_load_dword v84, v16, s[0:1] offset:224 nt
	s_nop 0
	s_nop 0
	s_nop 0

; __device__ __forceinline__ void cvt_load(const CvtJob& J, f32x4 (&cv)[8], int wave, int lane) {
;     const int nblk = (J.N + 255) / 256, kb = J.item / nblk, nb = J.item % nblk, k0 = 64 * kb, n0 = 256 * nb;
;     const bool nok = (n0 + 4 * lane) < J.N;
; #pragma unroll
;     for (int i = 0; i < 8; ++i) { const int k = k0 + wave + 8 * i;
;         cv[i] = nok ? *(const f32x4*)(J.W + (size_t)k * J.N + n0 + 4 * lane) : (f32x4){0.f, 0.f, 0.f, 0.f};
;         if (J.gam) cv[i] = cv[i] * J.gam[k]; }
; }
; __global__ void __launch_bounds__(512, 2) mega_fwd(Args args) {
;     ...
;                 it += G; CVT_DECODE_P0(nxt, it); if (nxt.ok) cvt_load(nxt, cv, wave, lane);
.LBB0_98:
	s_xor_b64 s[4:5], s[4:5], -1
	s_and_b64 vcc, exec, s[4:5]
	s_cbranch_vccnz .LBB0_131
	s_add_i32 s6, s97, 0xff
	s_ashr_i32 s7, s6, 31
	s_lshr_b32 s7, s7, 24
	s_add_i32 s6, s6, s7
	s_ashr_i32 s6, s6, 8
	s_abs_i32 s7, s6
	v_cvt_f32_u32_e32 v0, s7
	s_sub_i32 s68, 0, s7
	s_abs_i32 s8, s33
	s_xor_b32 s9, s33, s6
	v_rcp_iflag_f32_e32 v0, v0
	s_ashr_i32 s9, s9, 31
	v_mov_b32_e32 v17, v16
	v_mov_b32_e32 v18, v16
	v_mul_f32_e32 v0, 0x4f7ffffe, v0
	v_cvt_u32_f32_e32 v0, v0
	v_mov_b32_e32 v19, v16
	v_lshlrev_b32_e32 v40, 2, v36
	v_readfirstlane_b32 s69, v0
	s_mul_i32 s68, s68, s69
	s_mul_hi_u32 s68, s69, s68
	s_add_i32 s69, s69, s68
	s_mul_hi_u32 s68, s8, s69
	s_mul_i32 s69, s68, s7
	s_sub_i32 s8, s8, s69
	s_add_i32 s70, s68, 1
	s_sub_i32 s69, s8, s7
	s_cmp_ge_u32 s8, s7
	s_cselect_b32 s68, s70, s68
	s_cselect_b32 s8, s69, s8
	s_add_i32 s69, s68, 1
	s_cmp_ge_u32 s8, s7
	s_cselect_b32 s7, s69, s68
	s_xor_b32 s7, s7, s9
	s_sub_i32 s7, s7, s9
	s_mul_i32 s6, s7, s6
	s_sub_i32 s6, s33, s6
	s_lshl_b32 s70, s6, 8
	s_lshl_b32 s7, s7, 6
	v_readlane_b32 s8, v238, 37
	v_or_b32_e32 v0, s70, v36
	s_add_i32 s68, s7, s8
	v_cmp_gt_i32_e64 s[6:7], s97, v0
	v_mov_b64_e32 v[0:1], v[16:17]
	s_ashr_i32 s71, s70, 31
	v_mov_b64_e32 v[2:3], v[18:19]
	s_and_saveexec_b64 s[8:9], s[6:7]
	s_cbranch_execz .LBB0_101
	s_ashr_i32 s69, s68, 31
	s_mul_hi_u32 s72, s68, s97
	s_mul_i32 s69, s69, s97
	s_add_i32 s73, s72, s69
	s_mul_i32 s72, s68, s97
	s_lshl_b64 s[72:73], s[72:73], 2
	s_add_u32 s69, s2, s72
	s_addc_u32 s84, s3, s73
	s_lshl_b64 s[72:73], s[70:71], 2
	s_add_u32 s72, s69, s72
	s_addc_u32 s73, s84, s73
	global_load_dwordx4 v[0:3], v40, s[72:73] nt
.LBB0_101:
	s_or_b64 exec, exec, s[8:9]
	s_cmp_lg_u64 s[92:93], 0
	s_cselect_b64 s[72:73], -1, 0
	s_cmp_eq_u64 s[92:93], 0
	s_cbranch_scc1 .LBB0_103
	s_ashr_i32 s69, s68, 31
	s_lshl_b64 s[8:9], s[68:69], 2
	s_add_u32 s8, s92, s8
	s_addc_u32 s9, s93, s9
	global_load_dword v70, v16, s[8:9] nt
	s_nop 0
	s_nop 0
	s_nop 0
.LBB0_103:
	v_mov_b32_e32 v17, v16
	v_mov_b32_e32 v18, v16
	v_mov_b32_e32 v19, v16
	v_mov_b64_e32 v[4:5], v[16:17]
	v_mov_b64_e32 v[6:7], v[18:19]
	s_and_saveexec_b64 s[8:9], s[6:7]
	s_cbranch_execz .LBB0_105
	s_add_i32 s69, s68, 8
	s_ashr_i32 s84, s69, 31
	s_mul_i32 s84, s84, s97
	s_mul_hi_u32 s85, s69, s97
	s_add_i32 s85, s85, s84
	s_mul_i32 s84, s69, s97
	s_lshl_b64 s[84:85], s[84:85], 2
	s_add_u32 s69, s2, s84
	s_addc_u32 s94, s3, s85
	s_lshl_b64 s[84:85], s[70:71], 2
	s_add_u32 s84, s69, s84
	s_addc_u32 s85, s94, s85
	global_load_dwordx4 v[4:7], v40, s[84:85] nt
.LBB0_105:
	s_or_b64 exec, exec, s[8:9]
	v_cndmask_b32_e64 v8, 0, 1, s[72:73]
	v_cmp_ne_u32_e64 s[8:9], 1, v8
	s_andn2_b64 vcc, exec, s[72:73]
	s_cbranch_vccnz .LBB0_107
	s_ashr_i32 s69, s68, 31
	s_lshl_b64 s[72:73], s[68:69], 2
	s_add_u32 s72, s92, s72
	s_addc_u32 s73, s93, s73
	global_load_dword v72, v16, s[72:73] offset:32 nt
	s_nop 0
	s_nop 0
	s_nop 0
.LBB0_107:
	v_mov_b32_e32 v17, v16
	v_mov_b32_e32 v18, v16
	v_mov_b32_e32 v19, v16
	v_mov_b64_e32 v[8:9], v[16:17]
	v_mov_b64_e32 v[10:11], v[18:19]
	s_and_saveexec_b64 s[72:73], s[6:7]
	s_cbranch_execz .LBB0_109
	s_add_i32 s69, s68, 16
	s_ashr_i32 s84, s69, 31
	s_mul_i32 s84, s84, s97
	s_mul_hi_u32 s85, s69, s97
	s_add_i32 s85, s85, s84
	s_mul_i32 s84, s69, s97
	s_lshl_b64 s[84:85], s[84:85], 2
	s_add_u32 s69, s2, s84
	s_addc_u32 s94, s3, s85
	s_lshl_b64 s[84:85], s[70:71], 2
	s_add_u32 s84, s69, s84
	s_addc_u32 s85, s94, s85
	global_load_dwordx4 v[8:11], v40, s[84:85] nt
.LBB0_109:
	s_or_b64 exec, exec, s[72:73]
	s_and_b64 vcc, exec, s[8:9]
	s_cbranch_vccnz .LBB0_111
	s_ashr_i32 s69, s68, 31
	s_lshl_b64 s[72:73], s[68:69], 2
	s_add_u32 s72, s92, s72
	s_addc_u32 s73, s93, s73
	global_load_dword v74, v16, s[72:73] offset:64 nt
	s_nop 0
	s_nop 0
	s_nop 0
; __device__ __forceinline__ void cvt_load(const CvtJob& J, f32x4 (&cv)[8], int wave, int lane) {
;     ...
;     for (int i = 0; i < 8; ++i) { const int k = k0 + wave + 8 * i;
;         cv[i] = nok ? *(const f32x4*)(J.W + (size_t)k * J.N + n0 + 4 * lane) : (f32x4){0.f, 0.f, 0.f, 0.f};
;         if (J.gam) cv[i] = cv[i] * J.gam[k]; }
.LBB0_111:
	v_mov_b32_e32 v17, v16
	v_mov_b32_e32 v18, v16
	v_mov_b32_e32 v19, v16
	v_mov_b64_e32 v[12:13], v[16:17]
	v_mov_b64_e32 v[14:15], v[18:19]
	s_and_saveexec_b64 s[72:73], s[6:7]
	s_cbranch_execz .LBB0_113
	s_add_i32 s69, s68, 24
	s_ashr_i32 s84, s69, 31
	s_mul_i32 s84, s84, s97
	s_mul_hi_u32 s85, s69, s97
	s_add_i32 s85, s85, s84
	s_mul_i32 s84, s69, s97
	s_lshl_b64 s[84:85], s[84:85], 2
	s_add_u32 s69, s2, s84
	s_addc_u32 s94, s3, s85
	s_lshl_b64 s[84:85], s[70:71], 2
	s_add_u32 s84, s69, s84
	s_addc_u32 s85, s94, s85
	global_load_dwordx4 v[12:15], v40, s[84:85] nt
.LBB0_113:
	s_or_b64 exec, exec, s[72:73]
	s_and_b64 vcc, exec, s[8:9]
	s_cbranch_vccnz .LBB0_115
	s_ashr_i32 s69, s68, 31
	s_lshl_b64 s[72:73], s[68:69], 2
	s_add_u32 s72, s92, s72
	s_addc_u32 s73, s93, s73
	global_load_dword v76, v16, s[72:73] offset:96 nt
	s_nop 0
	s_nop 0
	s_nop 0
.LBB0_115:
	v_mov_b32_e32 v18, v16
	v_mov_b32_e32 v19, v16
	v_mov_b32_e32 v17, v16
	v_mov_b64_e32 v[22:23], v[18:19]
	v_mov_b64_e32 v[20:21], v[16:17]
	s_and_saveexec_b64 s[72:73], s[6:7]
	s_cbranch_execz .LBB0_117
	s_add_i32 s69, s68, 32
	s_ashr_i32 s84, s69, 31
	s_mul_i32 s84, s84, s97
	s_mul_hi_u32 s85, s69, s97
	s_add_i32 s85, s85, s84
	s_mul_i32 s84, s69, s97
	s_lshl_b64 s[84:85], s[84:85], 2
	s_add_u32 s69, s2, s84
	s_addc_u32 s94, s3, s85
	s_lshl_b64 s[84:85], s[70:71], 2
	s_add_u32 s84, s69, s84
	s_addc_u32 s85, s94, s85
	global_load_dwordx4 v[20:23], v40, s[84:85] nt
.LBB0_117:
	s_or_b64 exec, exec, s[72:73]
	s_and_b64 vcc, exec, s[8:9]
	s_cbranch_vccnz .LBB0_119
	s_ashr_i32 s69, s68, 31
	s_lshl_b64 s[72:73], s[68:69], 2
	s_add_u32 s72, s92, s72
	s_addc_u32 s73, s93, s73
	global_load_dword v78, v16, s[72:73] offset:128 nt
	s_nop 0
	s_nop 0
	s_nop 0
.LBB0_119:
	v_mov_b32_e32 v18, v16
	v_mov_b32_e32 v19, v16
	v_mov_b32_e32 v17, v16
	v_mov_b64_e32 v[26:27], v[18:19]
	v_mov_b64_e32 v[24:25], v[16:17]
	s_and_saveexec_b64 s[72:73], s[6:7]
	s_cbranch_execz .LBB0_121
	s_add_i32 s69, s68, 40
	s_ashr_i32 s84, s69, 31
	s_mul_i32 s84, s84, s97
	s_mul_hi_u32 s85, s69, s97
	s_add_i32 s85, s85, s84
	s_mul_i32 s84, s69, s97
	s_lshl_b64 s[84:85], s[84:85], 2
	s_add_u32 s69, s2, s84
	s_addc_u32 s94, s3, s85
	s_lshl_b64 s[84:85], s[70:71], 2
	s_add_u32 s84, s69, s84
	s_addc_u32 s85, s94, s85
	global_load_dwordx4 v[24:27], v40, s[84:85] nt
.LBB0_121:
	s_or_b64 exec, exec, s[72:73]
	s_and_b64 vcc, exec, s[8:9]
	s_cbranch_vccnz .LBB0_123
	s_ashr_i32 s69, s68, 31
	s_lshl_b64 s[72:73], s[68:69], 2
	s_add_u32 s72, s92, s72
	s_addc_u32 s73, s93, s73
	global_load_dword v80, v16, s[72:73] offset:160 nt
	s_nop 0
	s_nop 0
	s_nop 0
.LBB0_123:
	v_mov_b32_e32 v18, v16
	v_mov_b32_e32 v19, v16
	v_mov_b32_e32 v17, v16
	v_mov_b64_e32 v[30:31], v[18:19]
	v_mov_b64_e32 v[28:29], v[16:17]
	s_and_saveexec_b64 s[72:73], s[6:7]
	s_cbranch_execz .LBB0_125
	s_add_i32 s69, s68, 48
	s_ashr_i32 s84, s69, 31
	s_mul_i32 s84, s84, s97
	s_mul_hi_u32 s85, s69, s97
	s_add_i32 s85, s85, s84
	s_mul_i32 s84, s69, s97
	s_lshl_b64 s[84:85], s[84:85], 2
	s_add_u32 s69, s2, s84
	s_addc_u32 s94, s3, s85
	s_lshl_b64 s[84:85], s[70:71], 2
	s_add_u32 s84, s69, s84
	s_addc_u32 s85, s94, s85
	global_load_dwordx4 v[28:31], v40, s[84:85] nt
.LBB0_125:
	s_or_b64 exec, exec, s[72:73]
	s_and_b64 vcc, exec, s[8:9]
	s_cbranch_vccnz .LBB0_127
	s_ashr_i32 s69, s68, 31
	s_lshl_b64 s[72:73], s[68:69], 2
	s_add_u32 s72, s92, s72
	s_addc_u32 s73, s93, s73
	global_load_dword v82, v16, s[72:73] offset:192 nt
	s_nop 0
	s_nop 0
	s_nop 0
.LBB0_127:
	v_mov_b32_e32 v18, v16
	v_mov_b32_e32 v19, v16
	v_mov_b32_e32 v17, v16
	v_mov_b64_e32 v[34:35], v[18:19]
	v_mov_b64_e32 v[32:33], v[16:17]
	s_and_saveexec_b64 s[72:73], s[6:7]
	s_cbranch_execz .LBB0_129
	s_add_i32 s6, s68, 56
	s_ashr_i32 s7, s6, 31
	s_mul_i32 s7, s7, s97
	s_mul_hi_u32 s69, s6, s97
	s_add_i32 s7, s69, s7
	s_mul_i32 s6, s6, s97
	s_lshl_b64 s[6:7], s[6:7], 2
	s_add_u32 s69, s2, s6
	s_addc_u32 s84, s3, s7
	s_lshl_b64 s[6:7], s[70:71], 2
	s_add_u32 s6, s69, s6
	s_addc_u32 s7, s84, s7
	global_load_dwordx4 v[32:35], v40, s[6:7] nt
.LBB0_129:
	s_or_b64 exec, exec, s[72:73]
	s_and_b64 vcc, exec, s[8:9]
	s_cbranch_vccnz .LBB0_131
	s_ashr_i32 s69, s68, 31
	s_lshl_b64 s[6:7], s[68:69], 2
	s_add_u32 s6, s92, s6
	s_addc_u32 s7, s93, s7
	global_load_dword v84, v16, s[6:7] offset:224 nt
	s_nop 0
	s_nop 0
	s_nop 0

; __device__ __forceinline__ unsigned pk2(float lo, float hi) { f32x2_t v = {lo, hi}; bf16x2_t b = __builtin_convertvector(v, bf16x2_t); return __builtin_bit_cast(unsigned, b); }
; __device__ __forceinline__ void rms_row2048(const float* xrow, const float* g, bf16_t* orow, int lane) {
;     const f32x4* xr = (const f32x4*)xrow + lane; const f32x4* gr = (const f32x4*)g + lane;
;     f32x4 v[8]; float s = 0.f;
; #pragma unroll
;     for (int j = 0; j < 8; ++j) { v[j] = xr[64 * j]; s += (v[j].x * v[j].x + v[j].y * v[j].y) + (v[j].z * v[j].z + v[j].w * v[j].w); }
;     const float r = rsqrtf(wave_sum(s) * (1.f / 2048.f) + EPS);
;     u32x2* o8 = (u32x2*)orow + lane;
; #pragma unroll
;     for (int j = 0; j < 8; ++j) { const f32x4 gg = gr[64 * j]; u32x2 w; w.x = pk2(v[j].x * r * gg.x, v[j].y * r * gg.y); w.y = pk2(v[j].z * r * gg.z, v[j].w * r * gg.w); o8[64 * j] = w; }
; __global__ void __launch_bounds__(512, 2) mega_fwd(Args args) {
;     ...
;         for (int m = gw; m < T; m += NGW) rms_row2048(x + (size_t)m * D, args.in[3], H + (size_t)m * D, lane);
.LBB0_257:
	s_or_b64 exec, exec, s[2:3]
	v_readlane_b32 s0, v238, 38
	s_cmpk_gt_i32 s0, 0x3fff
	v_readlane_b32 s1, v238, 39
	s_cbranch_scc1 .LBB0_260
	v_lshlrev_b32_e32 v0, 4, v184
	v_mov_b32_e32 v1, 0
	v_lshl_add_u64 v[16:17], s[58:59], 0, v[0:1]
	s_mov_b64 s[0:1], 0x1000
	v_lshl_add_u64 v[18:19], v[16:17], 0, s[0:1]
	s_mov_b64 s[0:1], 0x1400
	v_lshl_add_u64 v[20:21], v[16:17], 0, s[0:1]
	s_mov_b64 s[0:1], 0x1800
	v_lshl_add_u64 v[22:23], v[16:17], 0, s[0:1]
	v_readlane_b32 s0, v238, 38
	v_readlane_b32 s1, v238, 39
	s_mov_b32 s8, s0
	s_ashr_i32 s9, s0, 31
	s_lshl_b64 s[0:1], s[8:9], 12
	s_add_u32 s0, s86, s0
	v_lshlrev_b32_e32 v2, 3, v184
	v_mov_b32_e32 v3, v1
	s_addc_u32 s1, s87, s1
	v_lshl_add_u64 v[2:3], s[0:1], 0, v[2:3]
	s_mov_b64 s[0:1], 0x6800e00
	s_ashr_i32 s97, s96, 31
	v_lshl_add_u64 v[26:27], v[2:3], 0, s[0:1]
	s_lshl_b64 s[0:1], s[96:97], 12
	s_lshl_b64 s[4:5], s[8:9], 13
	s_add_u32 s4, s52, s4
	s_addc_u32 s5, s53, s5
	s_mov_b64 s[2:3], 0x1c00
	v_lshl_add_u64 v[0:1], s[4:5], 0, v[0:1]
	s_mov_b32 s6, s8
	v_lshl_add_u64 v[24:25], v[16:17], 0, s[2:3]
	v_lshl_add_u64 v[28:29], v[0:1], 0, s[2:3]
	s_lshl_b64 s[2:3], s[96:97], 13
	v_mov_b32_e32 v30, 0x358637bd
	s_mov_b32 s4, 0x800000
	v_writelane_b32 v238, s6, 38
	s_mov_b32 s5, s8
	s_nop 0
	v_writelane_b32 v238, s7, 39
	global_load_dwordx4 v[80:83], v[16:17], off nt
	global_load_dwordx4 v[84:87], v[16:17], off offset:1024 nt
	global_load_dwordx4 v[88:91], v[16:17], off offset:2048 nt
	global_load_dwordx4 v[92:95], v[16:17], off offset:3072 nt
	global_load_dwordx4 v[96:99], v[18:19], off nt
	global_load_dwordx4 v[100:103], v[20:21], off nt
	global_load_dwordx4 v[104:107], v[22:23], off nt
	global_load_dwordx4 v[108:111], v[24:25], off nt
	v_add_co_u32_e32 v144, vcc, 0xfffff000, v28
	global_load_dwordx4 v[112:115], v[28:29], off offset:-3072 nt
	global_load_dwordx4 v[116:119], v[28:29], off offset:-2048 nt
	global_load_dwordx4 v[120:123], v[28:29], off offset:-1024 nt
	v_addc_co_u32_e32 v145, vcc, -1, v29, vcc
	global_load_dwordx4 v[124:127], v[144:145], off offset:-3072 nt
	global_load_dwordx4 v[128:131], v[144:145], off offset:-2048 nt
	global_load_dwordx4 v[132:135], v[144:145], off offset:-1024 nt
	global_load_dwordx4 v[136:139], v[28:29], off offset:-4096 nt
	s_nop 0
	global_load_dwordx4 v[140:143], v[28:29], off nt
	s_add_i32 s5, s5, s96
	s_cmpk_lt_i32 s5, 0x4000
	v_lshl_add_u64 v[28:29], v[28:29], 0, s[2:3]
	s_cselect_b32 s16, 1, 0
	s_waitcnt vmcnt(0)
.LBB0_259:
	v_mov_b32_e32 v4, v112
	v_mov_b32_e32 v5, v113
	v_mov_b32_e32 v6, v114
	v_mov_b32_e32 v7, v115
	v_mov_b32_e32 v12, v116
	v_mov_b32_e32 v13, v117
	v_mov_b32_e32 v14, v118
	v_mov_b32_e32 v15, v119
	v_mov_b32_e32 v8, v120
	v_mov_b32_e32 v9, v121
	v_mov_b32_e32 v10, v122
	v_mov_b32_e32 v11, v123
	v_mov_b32_e32 v32, v124
	v_mov_b32_e32 v33, v125
	v_mov_b32_e32 v34, v126
	v_mov_b32_e32 v35, v127
	v_mov_b32_e32 v36, v128
	v_mov_b32_e32 v37, v129
	v_mov_b32_e32 v38, v130
	v_mov_b32_e32 v39, v131
	v_mov_b32_e32 v40, v132
	v_mov_b32_e32 v41, v133
	v_mov_b32_e32 v42, v134
	v_mov_b32_e32 v43, v135
	v_mov_b32_e32 v44, v136
	v_mov_b32_e32 v45, v137
	v_mov_b32_e32 v46, v138
	v_mov_b32_e32 v47, v139
	v_mov_b32_e32 v0, v140
	v_mov_b32_e32 v1, v141
	v_mov_b32_e32 v2, v142
	v_mov_b32_e32 v3, v143
	s_mov_b32 s17, 0
	s_cmp_lg_u32 s16, 0
	s_cbranch_scc0 .Lp0r_nopref
	v_add_co_u32_e32 v144, vcc, 0xfffff000, v28
	global_load_dwordx4 v[112:115], v[28:29], off offset:-3072 nt
	global_load_dwordx4 v[116:119], v[28:29], off offset:-2048 nt
	global_load_dwordx4 v[120:123], v[28:29], off offset:-1024 nt
	v_addc_co_u32_e32 v145, vcc, -1, v29, vcc
	global_load_dwordx4 v[124:127], v[144:145], off offset:-3072 nt
	global_load_dwordx4 v[128:131], v[144:145], off offset:-2048 nt
	global_load_dwordx4 v[132:135], v[144:145], off offset:-1024 nt
	global_load_dwordx4 v[136:139], v[28:29], off offset:-4096 nt
	s_nop 0
	global_load_dwordx4 v[140:143], v[28:29], off nt
	s_add_i32 s5, s5, s96
	s_cmpk_lt_i32 s5, 0x4000
	v_lshl_add_u64 v[28:29], v[28:29], 0, s[2:3]
	s_cselect_b32 s16, 1, 0
	s_mov_b32 s17, 1

; __device__ __forceinline__ unsigned pk2(float lo, float hi) { f32x2_t v = {lo, hi}; bf16x2_t b = __builtin_convertvector(v, bf16x2_t); return __builtin_bit_cast(unsigned, b); }
; __device__ __forceinline__ float xor16_sum(float v) { float a = v, b = v; swap16(a, b); return a + b; }
; __device__ __forceinline__ float xor32_sum(float v) { float a = v, b = v; swap32(a, b); return a + b; }
;     __device__ __forceinline__ void operator()(const f32x4 (&acc)[2][2][4][2], const Unit& u, int wr, int wc, int fr, int fq) const {
;         const int row0 = u.pm * BM + wr * 64 + fr; constexpr int ldc = 2048; constexpr float alpha = 0.5f * ALPHA2;
;         bf16_t* const xb = (bf16_t*)(ws + XBOFF); __attribute__((address_space(1))) float* const ss = (__attribute__((address_space(1))) float*)(ws + SSOFF);
; #pragma unroll
;         for (int ai = 0; ai < 2; ++ai)
; #pragma unroll
;             for (int m = 0; m < 4; ++m) {
;                 const int row = row0 + ai * HALF + m * 16; float sq = 0.f;
; #pragma unroll
;                 for (int bj = 0; bj < 2; ++bj)
; #pragma unroll
;                     for (int n = 0; n < 2; ++n) {
;                         const size_t idx = (size_t)row * ldc + u.pn * BM + bj * HALF + wc * 32 + 8 * fq + 4 * n;
;                         const f32x4 b = *(const f32x4*)(base + idx);
;                         const f32x4 v = b + acc[ai][bj][m][n] * alpha;
;                         *(f32x4*)(out + idx) = v;
;                         if (NORM) { u32x2 w; w.x = pk2(v[0], v[1]); w.y = pk2(v[2], v[3]); *(u32x2*)(xb + idx) = w; sq += (v[0] * v[0] + v[1] * v[1]) + (v[2] * v[2] + v[3] * v[3]); }
;                     }
;                 if (NORM) { sq = xor16_sum(sq); sq = xor32_sum(sq); if (fq == 0) __hip_atomic_fetch_add(ss + row, sq, __ATOMIC_RELAXED, __HIP_MEMORY_SCOPE_AGENT); }
;             }
.LBB0_423:
	v_lshl_add_u32 v148, s14, 8, v137
	s_lshl_b32 s12, s16, 8
	s_ashr_i32 s13, s12, 31
	v_ashrrev_i32_e32 v149, 31, v148
	v_mov_b32_e32 v147, s13
	v_or_b32_e32 v146, s12, v136
	v_lshlrev_b64 v[154:155], 11, v[148:149]
	v_lshl_add_u64 v[158:159], v[154:155], 0, v[146:147]
	v_lshlrev_b64 v[160:161], 2, v[158:159]
	v_lshl_add_u64 v[162:163], s[52:53], 0, v[160:161]
	v_mov_b32_e32 v232, v162
	v_mov_b32_e32 v233, v163
	v_mov_b32_e32 v231, 0
	v_mov_b32_e32 v230, 0x0
	v_lshl_add_u64 v[228:229], v[232:233], 0, v[230:231]
	global_load_dwordx4 v[164:167], v[228:229], off nt
	global_load_dwordx4 v[168:171], v[228:229], off offset:16 nt
	global_load_dwordx4 v[172:175], v[228:229], off offset:512 nt
	global_load_dwordx4 v[176:179], v[228:229], off offset:528 nt
	v_mov_b32_e32 v230, 0x20000
	v_lshl_add_u64 v[228:229], v[232:233], 0, v[230:231]
	global_load_dwordx4 v[180:183], v[228:229], off nt
	global_load_dwordx4 v[188:191], v[228:229], off offset:16 nt
	global_load_dwordx4 v[192:195], v[228:229], off offset:512 nt
	global_load_dwordx4 v[196:199], v[228:229], off offset:528 nt
	v_mov_b32_e32 v230, 0x40000
	v_lshl_add_u64 v[228:229], v[232:233], 0, v[230:231]
	global_load_dwordx4 v[200:203], v[228:229], off nt
	global_load_dwordx4 v[204:207], v[228:229], off offset:16 nt
	global_load_dwordx4 v[208:211], v[228:229], off offset:512 nt
	global_load_dwordx4 v[212:215], v[228:229], off offset:528 nt
	v_mov_b32_e32 v230, 0x60000
	v_lshl_add_u64 v[228:229], v[232:233], 0, v[230:231]
	global_load_dwordx4 v[216:219], v[228:229], off nt
	global_load_dwordx4 v[220:223], v[228:229], off offset:16 nt
	global_load_dwordx4 v[224:227], v[228:229], off offset:512 nt
	global_load_dwordx4 v[234:237], v[228:229], off offset:528 nt
	s_nop 0
	v_lshlrev_b64 v[158:159], 1, v[158:159]
	s_nop 0
	s_waitcnt vmcnt(12)
	v_pk_fma_f32 v[126:127], v[126:127], 0.5, v[166:167] op_sel_hi:[1,0,1]
	v_pk_fma_f32 v[124:125], v[124:125], 0.5, v[164:165] op_sel_hi:[1,0,1]
	v_lshl_add_u64 v[154:155], s[30:31], 0, v[160:161]
	global_store_dwordx4 v[154:155], v[124:127], off
	v_cvt_pk_bf16_f32 v156, v124, v125
	v_cvt_pk_bf16_f32 v157, v126, v127
	v_mul_f32_e32 v125, v125, v125
	v_lshl_add_u64 v[160:161], s[40:41], 0, v[158:159]
	v_fmac_f32_e32 v125, v124, v124
	v_mul_f32_e32 v124, v127, v127
	global_store_dwordx2 v[160:161], v[156:157], off
	v_fmac_f32_e32 v124, v126, v126
	v_add_f32_e32 v156, v125, v124
	s_nop 0
	s_nop 0
	v_pk_fma_f32 v[122:123], v[122:123], 0.5, v[170:171] op_sel_hi:[1,0,1]
	v_pk_fma_f32 v[120:121], v[120:121], 0.5, v[168:169] op_sel_hi:[1,0,1]
	global_store_dwordx4 v[154:155], v[120:123], off offset:16
	v_cvt_pk_bf16_f32 v124, v120, v121
	v_or_b32_e32 v126, 8, v158
	v_mul_f32_e32 v121, v121, v121
	v_mov_b32_e32 v127, v159
	v_fmac_f32_e32 v121, v120, v120
	v_mul_f32_e32 v120, v123, v123
	v_cvt_pk_bf16_f32 v125, v122, v123
	v_lshl_add_u64 v[126:127], s[40:41], 0, v[126:127]
	v_fmac_f32_e32 v120, v122, v122
	global_store_dwordx2 v[126:127], v[124:125], off
	v_add_f32_e32 v120, v121, v120
	v_add_f32_e32 v124, v156, v120
	s_nop 0
	s_nop 0
	v_pk_fma_f32 v[118:119], v[118:119], 0.5, v[174:175] op_sel_hi:[1,0,1]
	v_pk_fma_f32 v[116:117], v[116:117], 0.5, v[172:173] op_sel_hi:[1,0,1]
	global_store_dwordx4 v[154:155], v[116:119], off offset:512
	v_cvt_pk_bf16_f32 v120, v116, v117
	v_or_b32_e32 v122, 0x100, v158
	v_mul_f32_e32 v117, v117, v117
	v_mov_b32_e32 v123, v159
	v_fmac_f32_e32 v117, v116, v116
	v_mul_f32_e32 v116, v119, v119
	v_cvt_pk_bf16_f32 v121, v118, v119
	v_lshl_add_u64 v[122:123], s[40:41], 0, v[122:123]
	v_fmac_f32_e32 v116, v118, v118
	global_store_dwordx2 v[122:123], v[120:121], off
	v_add_f32_e32 v116, v117, v116
	v_add_f32_e32 v120, v124, v116
	s_nop 0
	v_or_b32_e32 v158, 0x108, v158
	s_nop 0
	v_pk_fma_f32 v[114:115], v[114:115], 0.5, v[178:179] op_sel_hi:[1,0,1]
	v_pk_fma_f32 v[112:113], v[112:113], 0.5, v[176:177] op_sel_hi:[1,0,1]
	v_mov_b32_e32 v230, 0x100000
	v_lshl_add_u64 v[228:229], v[232:233], 0, v[230:231]
	global_load_dwordx4 v[164:167], v[228:229], off nt
	global_load_dwordx4 v[168:171], v[228:229], off offset:16 nt
	global_load_dwordx4 v[172:175], v[228:229], off offset:512 nt
	global_load_dwordx4 v[176:179], v[228:229], off offset:528 nt
	global_store_dwordx4 v[154:155], v[112:115], off offset:528
	v_cvt_pk_bf16_f32 v116, v112, v113
	v_cvt_pk_bf16_f32 v117, v114, v115
	v_mul_f32_e32 v113, v113, v113
	v_fmac_f32_e32 v113, v112, v112
	v_mul_f32_e32 v112, v115, v115
	v_fmac_f32_e32 v112, v114, v114
	v_add_f32_e32 v112, v113, v112
	v_add_f32_e32 v112, v120, v112
	v_mov_b32_e32 v113, v112
	s_nop 1
	v_permlane16_swap_b32 v112, v113
	v_lshl_add_u64 v[118:119], s[40:41], 0, v[158:159]
	v_add_f32_e32 v112, v112, v113
	v_mov_b32_e32 v113, v112
	global_store_dwordx2 v[118:119], v[116:117], off
	s_nop 1
	v_permlane32_swap_b32 v112, v113
	s_and_saveexec_b64 s[12:13], s[2:3]
	s_cbranch_execz .LBB0_425
	v_lshl_add_u64 v[114:115], v[148:149], 2, s[90:91]
	v_add_f32_e32 v112, v112, v113
	global_atomic_add_f32 v[114:115], v112, off
; __device__ __forceinline__ unsigned pk2(float lo, float hi) { f32x2_t v = {lo, hi}; bf16x2_t b = __builtin_convertvector(v, bf16x2_t); return __builtin_bit_cast(unsigned, b); }
; __device__ __forceinline__ float xor16_sum(float v) { float a = v, b = v; swap16(a, b); return a + b; }
; __device__ __forceinline__ float xor32_sum(float v) { float a = v, b = v; swap32(a, b); return a + b; }
;     __device__ __forceinline__ void operator()(const f32x4 (&acc)[2][2][4][2], const Unit& u, int wr, int wc, int fr, int fq) const {
;     ...
;                 const int row = row0 + ai * HALF + m * 16; float sq = 0.f;
; #pragma unroll
;                 for (int bj = 0; bj < 2; ++bj)
; #pragma unroll
;                     for (int n = 0; n < 2; ++n) {
;                         const size_t idx = (size_t)row * ldc + u.pn * BM + bj * HALF + wc * 32 + 8 * fq + 4 * n;
;                         const f32x4 b = *(const f32x4*)(base + idx);
;                         const f32x4 v = b + acc[ai][bj][m][n] * alpha;
;                         *(f32x4*)(out + idx) = v;
;                         if (NORM) { u32x2 w; w.x = pk2(v[0], v[1]); w.y = pk2(v[2], v[3]); *(u32x2*)(xb + idx) = w; sq += (v[0] * v[0] + v[1] * v[1]) + (v[2] * v[2] + v[3] * v[3]); }
;                     }
;                 if (NORM) { sq = xor16_sum(sq); sq = xor32_sum(sq); if (fq == 0) __hip_atomic_fetch_add(ss + row, sq, __ATOMIC_RELAXED, __HIP_MEMORY_SCOPE_AGENT); }
.LBB0_425:
	s_or_b64 exec, exec, s[12:13]
	v_or_b32_e32 v112, 16, v148
	v_ashrrev_i32_e32 v113, 31, v112
	v_lshlrev_b64 v[114:115], 11, v[112:113]
	v_lshl_add_u64 v[118:119], v[114:115], 0, v[146:147]
	v_lshlrev_b64 v[120:121], 2, v[118:119]
	v_lshl_add_u64 v[122:123], s[52:53], 0, v[120:121]
	s_nop 0
	v_lshlrev_b64 v[118:119], 1, v[118:119]
	s_nop 0
	s_waitcnt vmcnt(20)
	v_pk_fma_f32 v[110:111], v[110:111], 0.5, v[182:183] op_sel_hi:[1,0,1]
	v_pk_fma_f32 v[108:109], v[108:109], 0.5, v[180:181] op_sel_hi:[1,0,1]
	v_lshl_add_u64 v[114:115], s[30:31], 0, v[120:121]
	global_store_dwordx4 v[114:115], v[108:111], off
	v_cvt_pk_bf16_f32 v116, v108, v109
	v_cvt_pk_bf16_f32 v117, v110, v111
	v_mul_f32_e32 v109, v109, v109
	v_lshl_add_u64 v[120:121], s[40:41], 0, v[118:119]
	v_fmac_f32_e32 v109, v108, v108
	v_mul_f32_e32 v108, v111, v111
	global_store_dwordx2 v[120:121], v[116:117], off
	v_fmac_f32_e32 v108, v110, v110
	v_add_f32_e32 v116, v109, v108
	s_nop 0
	s_nop 0
	v_pk_fma_f32 v[106:107], v[106:107], 0.5, v[190:191] op_sel_hi:[1,0,1]
	v_pk_fma_f32 v[104:105], v[104:105], 0.5, v[188:189] op_sel_hi:[1,0,1]
	global_store_dwordx4 v[114:115], v[104:107], off offset:16
	v_cvt_pk_bf16_f32 v108, v104, v105
	v_or_b32_e32 v110, 8, v118
	v_mul_f32_e32 v105, v105, v105
	v_mov_b32_e32 v111, v119
	v_fmac_f32_e32 v105, v104, v104
	v_mul_f32_e32 v104, v107, v107
	v_cvt_pk_bf16_f32 v109, v106, v107
	v_lshl_add_u64 v[110:111], s[40:41], 0, v[110:111]
	v_fmac_f32_e32 v104, v106, v106
	global_store_dwordx2 v[110:111], v[108:109], off
	v_add_f32_e32 v104, v105, v104
	v_add_f32_e32 v108, v116, v104
	s_nop 0
	s_nop 0
	v_pk_fma_f32 v[102:103], v[102:103], 0.5, v[194:195] op_sel_hi:[1,0,1]
	v_pk_fma_f32 v[100:101], v[100:101], 0.5, v[192:193] op_sel_hi:[1,0,1]
	global_store_dwordx4 v[114:115], v[100:103], off offset:512
	v_cvt_pk_bf16_f32 v104, v100, v101
	v_or_b32_e32 v106, 0x100, v118
	v_mul_f32_e32 v101, v101, v101
	v_mov_b32_e32 v107, v119
	v_fmac_f32_e32 v101, v100, v100
	v_mul_f32_e32 v100, v103, v103
	v_cvt_pk_bf16_f32 v105, v102, v103
	v_lshl_add_u64 v[106:107], s[40:41], 0, v[106:107]
	v_fmac_f32_e32 v100, v102, v102
	global_store_dwordx2 v[106:107], v[104:105], off
	v_add_f32_e32 v100, v101, v100
	v_add_f32_e32 v104, v108, v100
	s_nop 0
	v_or_b32_e32 v118, 0x108, v118
	s_nop 0
	v_pk_fma_f32 v[98:99], v[98:99], 0.5, v[198:199] op_sel_hi:[1,0,1]
	v_pk_fma_f32 v[96:97], v[96:97], 0.5, v[196:197] op_sel_hi:[1,0,1]
	v_mov_b32_e32 v230, 0x120000
	v_lshl_add_u64 v[228:229], v[232:233], 0, v[230:231]
	global_load_dwordx4 v[180:183], v[228:229], off nt
	global_load_dwordx4 v[188:191], v[228:229], off offset:16 nt
	global_load_dwordx4 v[192:195], v[228:229], off offset:512 nt
	global_load_dwordx4 v[196:199], v[228:229], off offset:528 nt
	global_store_dwordx4 v[114:115], v[96:99], off offset:528
	v_cvt_pk_bf16_f32 v100, v96, v97
	v_cvt_pk_bf16_f32 v101, v98, v99
	v_mul_f32_e32 v97, v97, v97
	v_fmac_f32_e32 v97, v96, v96
	v_mul_f32_e32 v96, v99, v99
	v_fmac_f32_e32 v96, v98, v98
	v_add_f32_e32 v96, v97, v96
	v_add_f32_e32 v96, v104, v96
	v_mov_b32_e32 v97, v96
	s_nop 1
	v_permlane16_swap_b32 v96, v97
	v_lshl_add_u64 v[102:103], s[40:41], 0, v[118:119]
	v_add_f32_e32 v96, v96, v97
	v_mov_b32_e32 v97, v96
	global_store_dwordx2 v[102:103], v[100:101], off
	s_nop 1
	v_permlane32_swap_b32 v96, v97
	s_and_saveexec_b64 s[12:13], s[2:3]
	s_cbranch_execz .LBB0_427
	v_lshl_add_u64 v[98:99], v[112:113], 2, s[90:91]
	v_add_f32_e32 v96, v96, v97
	global_atomic_add_f32 v[98:99], v96, off
; __device__ __forceinline__ unsigned pk2(float lo, float hi) { f32x2_t v = {lo, hi}; bf16x2_t b = __builtin_convertvector(v, bf16x2_t); return __builtin_bit_cast(unsigned, b); }
; __device__ __forceinline__ float xor16_sum(float v) { float a = v, b = v; swap16(a, b); return a + b; }
; __device__ __forceinline__ float xor32_sum(float v) { float a = v, b = v; swap32(a, b); return a + b; }
;     __device__ __forceinline__ void operator()(const f32x4 (&acc)[2][2][4][2], const Unit& u, int wr, int wc, int fr, int fq) const {
;     ...
;                 const int row = row0 + ai * HALF + m * 16; float sq = 0.f;
; #pragma unroll
;                 for (int bj = 0; bj < 2; ++bj)
; #pragma unroll
;                     for (int n = 0; n < 2; ++n) {
;                         const size_t idx = (size_t)row * ldc + u.pn * BM + bj * HALF + wc * 32 + 8 * fq + 4 * n;
;                         const f32x4 b = *(const f32x4*)(base + idx);
;                         const f32x4 v = b + acc[ai][bj][m][n] * alpha;
;                         *(f32x4*)(out + idx) = v;
;                         if (NORM) { u32x2 w; w.x = pk2(v[0], v[1]); w.y = pk2(v[2], v[3]); *(u32x2*)(xb + idx) = w; sq += (v[0] * v[0] + v[1] * v[1]) + (v[2] * v[2] + v[3] * v[3]); }
;                     }
;                 if (NORM) { sq = xor16_sum(sq); sq = xor32_sum(sq); if (fq == 0) __hip_atomic_fetch_add(ss + row, sq, __ATOMIC_RELAXED, __HIP_MEMORY_SCOPE_AGENT); }
.LBB0_427:
	s_or_b64 exec, exec, s[12:13]
	v_or_b32_e32 v96, 32, v148
	v_ashrrev_i32_e32 v97, 31, v96
	v_lshlrev_b64 v[98:99], 11, v[96:97]
	v_lshl_add_u64 v[102:103], v[98:99], 0, v[146:147]
	v_lshlrev_b64 v[104:105], 2, v[102:103]
	v_lshl_add_u64 v[106:107], s[52:53], 0, v[104:105]
	s_nop 0
	v_lshlrev_b64 v[102:103], 1, v[102:103]
	s_nop 0
	s_waitcnt vmcnt(28)
	v_pk_fma_f32 v[94:95], v[94:95], 0.5, v[202:203] op_sel_hi:[1,0,1]
	v_pk_fma_f32 v[92:93], v[92:93], 0.5, v[200:201] op_sel_hi:[1,0,1]
	v_lshl_add_u64 v[98:99], s[30:31], 0, v[104:105]
	global_store_dwordx4 v[98:99], v[92:95], off
	v_cvt_pk_bf16_f32 v100, v92, v93
	v_cvt_pk_bf16_f32 v101, v94, v95
	v_mul_f32_e32 v93, v93, v93
	v_lshl_add_u64 v[104:105], s[40:41], 0, v[102:103]
	v_fmac_f32_e32 v93, v92, v92
	v_mul_f32_e32 v92, v95, v95
	global_store_dwordx2 v[104:105], v[100:101], off
	v_fmac_f32_e32 v92, v94, v94
	v_add_f32_e32 v100, v93, v92
	s_nop 0
	s_nop 0
	v_pk_fma_f32 v[90:91], v[90:91], 0.5, v[206:207] op_sel_hi:[1,0,1]
	v_pk_fma_f32 v[88:89], v[88:89], 0.5, v[204:205] op_sel_hi:[1,0,1]
	global_store_dwordx4 v[98:99], v[88:91], off offset:16
	v_cvt_pk_bf16_f32 v92, v88, v89
	v_or_b32_e32 v94, 8, v102
	v_mul_f32_e32 v89, v89, v89
	v_mov_b32_e32 v95, v103
	v_fmac_f32_e32 v89, v88, v88
	v_mul_f32_e32 v88, v91, v91
	v_cvt_pk_bf16_f32 v93, v90, v91
	v_lshl_add_u64 v[94:95], s[40:41], 0, v[94:95]
	v_fmac_f32_e32 v88, v90, v90
	global_store_dwordx2 v[94:95], v[92:93], off
	v_add_f32_e32 v88, v89, v88
	v_add_f32_e32 v92, v100, v88
	s_nop 0
	s_nop 0
	v_pk_fma_f32 v[86:87], v[86:87], 0.5, v[210:211] op_sel_hi:[1,0,1]
	v_pk_fma_f32 v[84:85], v[84:85], 0.5, v[208:209] op_sel_hi:[1,0,1]
	global_store_dwordx4 v[98:99], v[84:87], off offset:512
	v_cvt_pk_bf16_f32 v88, v84, v85
	v_or_b32_e32 v90, 0x100, v102
	v_mul_f32_e32 v85, v85, v85
	v_mov_b32_e32 v91, v103
	v_fmac_f32_e32 v85, v84, v84
	v_mul_f32_e32 v84, v87, v87
	v_cvt_pk_bf16_f32 v89, v86, v87
	v_lshl_add_u64 v[90:91], s[40:41], 0, v[90:91]
	v_fmac_f32_e32 v84, v86, v86
	global_store_dwordx2 v[90:91], v[88:89], off
	v_add_f32_e32 v84, v85, v84
	v_add_f32_e32 v88, v92, v84
	s_nop 0
	v_or_b32_e32 v102, 0x108, v102
	s_nop 0
	v_pk_fma_f32 v[82:83], v[82:83], 0.5, v[214:215] op_sel_hi:[1,0,1]
	v_pk_fma_f32 v[80:81], v[80:81], 0.5, v[212:213] op_sel_hi:[1,0,1]
	v_mov_b32_e32 v230, 0x140000
	v_lshl_add_u64 v[228:229], v[232:233], 0, v[230:231]
	global_load_dwordx4 v[200:203], v[228:229], off nt
	global_load_dwordx4 v[204:207], v[228:229], off offset:16 nt
	global_load_dwordx4 v[208:211], v[228:229], off offset:512 nt
	global_load_dwordx4 v[212:215], v[228:229], off offset:528 nt
	global_store_dwordx4 v[98:99], v[80:83], off offset:528
	v_cvt_pk_bf16_f32 v84, v80, v81
	v_cvt_pk_bf16_f32 v85, v82, v83
	v_mul_f32_e32 v81, v81, v81
	v_fmac_f32_e32 v81, v80, v80
	v_mul_f32_e32 v80, v83, v83
	v_fmac_f32_e32 v80, v82, v82
	v_add_f32_e32 v80, v81, v80
	v_add_f32_e32 v80, v88, v80
	v_mov_b32_e32 v81, v80
	s_nop 1
	v_permlane16_swap_b32 v80, v81
	v_lshl_add_u64 v[86:87], s[40:41], 0, v[102:103]
	v_add_f32_e32 v80, v80, v81
	v_mov_b32_e32 v81, v80
	global_store_dwordx2 v[86:87], v[84:85], off
	s_nop 1
	v_permlane32_swap_b32 v80, v81
	s_and_saveexec_b64 s[12:13], s[2:3]
	s_cbranch_execz .LBB0_429
	v_lshl_add_u64 v[82:83], v[96:97], 2, s[90:91]
	v_add_f32_e32 v80, v80, v81
	global_atomic_add_f32 v[82:83], v80, off
.LBB0_429:
	s_or_b64 exec, exec, s[12:13]
	v_or_b32_e32 v80, 48, v148
	v_ashrrev_i32_e32 v81, 31, v80
	v_lshlrev_b64 v[82:83], 11, v[80:81]
	v_lshl_add_u64 v[86:87], v[82:83], 0, v[146:147]
	v_lshlrev_b64 v[88:89], 2, v[86:87]
	v_lshl_add_u64 v[90:91], s[52:53], 0, v[88:89]
	s_nop 0
	v_lshlrev_b64 v[86:87], 1, v[86:87]
	s_nop 0
	s_waitcnt vmcnt(36)
	v_pk_fma_f32 v[78:79], v[78:79], 0.5, v[218:219] op_sel_hi:[1,0,1]
	v_pk_fma_f32 v[76:77], v[76:77], 0.5, v[216:217] op_sel_hi:[1,0,1]
	v_lshl_add_u64 v[82:83], s[30:31], 0, v[88:89]
	global_store_dwordx4 v[82:83], v[76:79], off
	v_cvt_pk_bf16_f32 v84, v76, v77
	v_cvt_pk_bf16_f32 v85, v78, v79
	v_mul_f32_e32 v77, v77, v77
	v_lshl_add_u64 v[88:89], s[40:41], 0, v[86:87]
	v_fmac_f32_e32 v77, v76, v76
	v_mul_f32_e32 v76, v79, v79
	global_store_dwordx2 v[88:89], v[84:85], off
	v_fmac_f32_e32 v76, v78, v78
	v_add_f32_e32 v84, v77, v76
	s_nop 0
	s_nop 0
	v_pk_fma_f32 v[74:75], v[74:75], 0.5, v[222:223] op_sel_hi:[1,0,1]
	v_pk_fma_f32 v[72:73], v[72:73], 0.5, v[220:221] op_sel_hi:[1,0,1]
	global_store_dwordx4 v[82:83], v[72:75], off offset:16
	v_cvt_pk_bf16_f32 v76, v72, v73
	v_or_b32_e32 v78, 8, v86
	v_mul_f32_e32 v73, v73, v73
	v_mov_b32_e32 v79, v87
	v_fmac_f32_e32 v73, v72, v72
	v_mul_f32_e32 v72, v75, v75
	v_cvt_pk_bf16_f32 v77, v74, v75
	v_lshl_add_u64 v[78:79], s[40:41], 0, v[78:79]
	v_fmac_f32_e32 v72, v74, v74
	global_store_dwordx2 v[78:79], v[76:77], off
	v_add_f32_e32 v72, v73, v72
	v_add_f32_e32 v76, v84, v72
	s_nop 0
	s_nop 0
	v_pk_fma_f32 v[70:71], v[70:71], 0.5, v[226:227] op_sel_hi:[1,0,1]
	v_pk_fma_f32 v[68:69], v[68:69], 0.5, v[224:225] op_sel_hi:[1,0,1]
	global_store_dwordx4 v[82:83], v[68:71], off offset:512
	v_cvt_pk_bf16_f32 v72, v68, v69
	v_or_b32_e32 v74, 0x100, v86
	v_mul_f32_e32 v69, v69, v69
	v_mov_b32_e32 v75, v87
	v_fmac_f32_e32 v69, v68, v68
	v_mul_f32_e32 v68, v71, v71
	v_cvt_pk_bf16_f32 v73, v70, v71
	v_lshl_add_u64 v[74:75], s[40:41], 0, v[74:75]
	v_fmac_f32_e32 v68, v70, v70
	global_store_dwordx2 v[74:75], v[72:73], off
	v_add_f32_e32 v68, v69, v68
	v_add_f32_e32 v72, v76, v68
	s_nop 0
	v_or_b32_e32 v86, 0x108, v86
	s_nop 0
	v_pk_fma_f32 v[66:67], v[66:67], 0.5, v[236:237] op_sel_hi:[1,0,1]
	v_pk_fma_f32 v[64:65], v[64:65], 0.5, v[234:235] op_sel_hi:[1,0,1]
	v_mov_b32_e32 v230, 0x160000
	v_lshl_add_u64 v[228:229], v[232:233], 0, v[230:231]
	global_load_dwordx4 v[216:219], v[228:229], off nt
	global_load_dwordx4 v[220:223], v[228:229], off offset:16 nt
	global_load_dwordx4 v[224:227], v[228:229], off offset:512 nt
	global_load_dwordx4 v[234:237], v[228:229], off offset:528 nt
	global_store_dwordx4 v[82:83], v[64:67], off offset:528
	v_cvt_pk_bf16_f32 v68, v64, v65
	v_cvt_pk_bf16_f32 v69, v66, v67
	v_mul_f32_e32 v65, v65, v65
	v_fmac_f32_e32 v65, v64, v64
	v_mul_f32_e32 v64, v67, v67
	v_fmac_f32_e32 v64, v66, v66
	v_add_f32_e32 v64, v65, v64
	v_add_f32_e32 v64, v72, v64
	v_mov_b32_e32 v65, v64
	s_nop 1
	v_permlane16_swap_b32 v64, v65
	v_lshl_add_u64 v[70:71], s[40:41], 0, v[86:87]
	v_add_f32_e32 v64, v64, v65
	v_mov_b32_e32 v65, v64
	global_store_dwordx2 v[70:71], v[68:69], off
	s_nop 1
	v_permlane32_swap_b32 v64, v65
	s_and_saveexec_b64 s[12:13], s[2:3]
	s_cbranch_execz .LBB0_431
	v_lshl_add_u64 v[66:67], v[80:81], 2, s[90:91]
	v_add_f32_e32 v64, v64, v65
	global_atomic_add_f32 v[66:67], v64, off

; __device__ __forceinline__ unsigned pk2(float lo, float hi) { f32x2_t v = {lo, hi}; bf16x2_t b = __builtin_convertvector(v, bf16x2_t); return __builtin_bit_cast(unsigned, b); }
; __device__ __forceinline__ float xor16_sum(float v) { float a = v, b = v; swap16(a, b); return a + b; }
; __device__ __forceinline__ float xor32_sum(float v) { float a = v, b = v; swap32(a, b); return a + b; }
;     __device__ __forceinline__ void operator()(const f32x4 (&acc)[2][2][4][2], const Unit& u, int wr, int wc, int fr, int fq) const {
;     ...
;                 const int row = row0 + ai * HALF + m * 16; float sq = 0.f;
; #pragma unroll
;                 for (int bj = 0; bj < 2; ++bj)
; #pragma unroll
;                     for (int n = 0; n < 2; ++n) {
;                         const size_t idx = (size_t)row * ldc + u.pn * BM + bj * HALF + wc * 32 + 8 * fq + 4 * n;
;                         const f32x4 b = *(const f32x4*)(base + idx);
;                         const f32x4 v = b + acc[ai][bj][m][n] * alpha;
;                         *(f32x4*)(out + idx) = v;
;                         if (NORM) { u32x2 w; w.x = pk2(v[0], v[1]); w.y = pk2(v[2], v[3]); *(u32x2*)(xb + idx) = w; sq += (v[0] * v[0] + v[1] * v[1]) + (v[2] * v[2] + v[3] * v[3]); }
;                     }
;                 if (NORM) { sq = xor16_sum(sq); sq = xor32_sum(sq); if (fq == 0) __hip_atomic_fetch_add(ss + row, sq, __ATOMIC_RELAXED, __HIP_MEMORY_SCOPE_AGENT); }
.LBB0_1208:
	v_lshl_add_u32 v148, s12, 8, v137
	s_lshl_b32 s12, s44, 8
	s_ashr_i32 s13, s12, 31
	v_ashrrev_i32_e32 v149, 31, v148
	v_mov_b32_e32 v147, s13
	v_or_b32_e32 v146, s12, v136
	v_lshlrev_b64 v[154:155], 11, v[148:149]
	v_lshl_add_u64 v[158:159], v[154:155], 0, v[146:147]
	v_lshl_add_u64 v[160:161], v[158:159], 2, s[30:31]
	v_mov_b32_e32 v232, v160
	v_mov_b32_e32 v233, v161
	v_mov_b32_e32 v231, 0
	v_mov_b32_e32 v230, 0x0
	v_lshl_add_u64 v[228:229], v[232:233], 0, v[230:231]
	global_load_dwordx4 v[164:167], v[228:229], off nt
	global_load_dwordx4 v[168:171], v[228:229], off offset:16 nt
	global_load_dwordx4 v[172:175], v[228:229], off offset:512 nt
	global_load_dwordx4 v[176:179], v[228:229], off offset:528 nt
	v_mov_b32_e32 v230, 0x20000
	v_lshl_add_u64 v[228:229], v[232:233], 0, v[230:231]
	global_load_dwordx4 v[180:183], v[228:229], off nt
	global_load_dwordx4 v[188:191], v[228:229], off offset:16 nt
	global_load_dwordx4 v[192:195], v[228:229], off offset:512 nt
	global_load_dwordx4 v[196:199], v[228:229], off offset:528 nt
	v_mov_b32_e32 v230, 0x40000
	v_lshl_add_u64 v[228:229], v[232:233], 0, v[230:231]
	global_load_dwordx4 v[200:203], v[228:229], off nt
	global_load_dwordx4 v[204:207], v[228:229], off offset:16 nt
	global_load_dwordx4 v[208:211], v[228:229], off offset:512 nt
	global_load_dwordx4 v[212:215], v[228:229], off offset:528 nt
	v_mov_b32_e32 v230, 0x60000
	v_lshl_add_u64 v[228:229], v[232:233], 0, v[230:231]
	global_load_dwordx4 v[216:219], v[228:229], off nt
	global_load_dwordx4 v[220:223], v[228:229], off offset:16 nt
	global_load_dwordx4 v[224:227], v[228:229], off offset:512 nt
	global_load_dwordx4 v[234:237], v[228:229], off offset:528 nt
	s_nop 0
	v_lshlrev_b64 v[158:159], 1, v[158:159]
	v_lshl_add_u64 v[162:163], s[6:7], 0, v[158:159]
	s_nop 0
	s_waitcnt vmcnt(12)
	v_pk_add_f32 v[126:127], v[126:127], v[166:167]
	v_pk_add_f32 v[124:125], v[124:125], v[164:165]
	v_cvt_pk_bf16_f32 v155, v126, v127
	v_cvt_pk_bf16_f32 v154, v124, v125
	global_store_dwordx4 v[160:161], v[124:127], off
	global_store_dwordx2 v[162:163], v[154:155], off
	s_nop 0
	v_or_b32_e32 v162, 8, v158
	v_mov_b32_e32 v163, v159
	v_lshl_add_u64 v[162:163], s[6:7], 0, v[162:163]
	v_mul_f32_e32 v125, v125, v125
	v_mul_f32_e32 v127, v127, v127
	v_fmac_f32_e32 v125, v124, v124
	v_fmac_f32_e32 v127, v126, v126
	v_add_f32_e32 v124, v125, v127
	s_nop 0
	v_pk_add_f32 v[122:123], v[122:123], v[170:171]
	v_pk_add_f32 v[120:121], v[120:121], v[168:169]
	v_cvt_pk_bf16_f32 v155, v122, v123
	v_cvt_pk_bf16_f32 v154, v120, v121
	global_store_dwordx4 v[160:161], v[120:123], off offset:16
	global_store_dwordx2 v[162:163], v[154:155], off
	s_nop 0
	v_or_b32_e32 v162, 0x100, v158
	v_mov_b32_e32 v163, v159
	v_lshl_add_u64 v[162:163], s[6:7], 0, v[162:163]
	v_mul_f32_e32 v121, v121, v121
	v_mul_f32_e32 v123, v123, v123
	v_fmac_f32_e32 v121, v120, v120
	v_fmac_f32_e32 v123, v122, v122
	v_add_f32_e32 v120, v121, v123
	v_add_f32_e32 v120, v124, v120
	v_or_b32_e32 v158, 0x108, v158
	v_lshl_add_u64 v[158:159], s[6:7], 0, v[158:159]
	s_nop 0
	v_pk_add_f32 v[118:119], v[118:119], v[174:175]
	v_pk_add_f32 v[116:117], v[116:117], v[172:173]
	v_cvt_pk_bf16_f32 v155, v118, v119
	v_cvt_pk_bf16_f32 v154, v116, v117
	global_store_dwordx4 v[160:161], v[116:119], off offset:512
	global_store_dwordx2 v[162:163], v[154:155], off
	s_nop 0
	v_mul_f32_e32 v117, v117, v117
	v_mul_f32_e32 v119, v119, v119
	v_fmac_f32_e32 v117, v116, v116
	v_fmac_f32_e32 v119, v118, v118
	v_add_f32_e32 v116, v117, v119
	v_add_f32_e32 v118, v120, v116
	s_nop 0
	v_pk_add_f32 v[114:115], v[114:115], v[178:179]
	v_pk_add_f32 v[112:113], v[112:113], v[176:177]
	v_mov_b32_e32 v230, 0x100000
	v_lshl_add_u64 v[228:229], v[232:233], 0, v[230:231]
	global_load_dwordx4 v[164:167], v[228:229], off nt
	global_load_dwordx4 v[168:171], v[228:229], off offset:16 nt
	global_load_dwordx4 v[172:175], v[228:229], off offset:512 nt
	global_load_dwordx4 v[176:179], v[228:229], off offset:528 nt
	global_store_dwordx4 v[160:161], v[112:115], off offset:528
	v_cvt_pk_bf16_f32 v116, v112, v113
	v_cvt_pk_bf16_f32 v117, v114, v115
	v_mul_f32_e32 v113, v113, v113
	v_mul_f32_e32 v115, v115, v115
	v_fmac_f32_e32 v113, v112, v112
	v_fmac_f32_e32 v115, v114, v114
	v_add_f32_e32 v112, v113, v115
	v_add_f32_e32 v112, v118, v112
	v_mov_b32_e32 v113, v112
	s_nop 1
	v_permlane16_swap_b32 v113, v112
	global_store_dwordx2 v[158:159], v[116:117], off
	v_add_f32_e32 v112, v113, v112
	v_mov_b32_e32 v113, v112
	s_nop 1
	v_permlane32_swap_b32 v113, v112
	s_and_saveexec_b64 s[12:13], s[2:3]
	s_cbranch_execz .LBB0_1210
	v_lshl_add_u64 v[114:115], v[148:149], 2, s[8:9]
	v_add_f32_e32 v112, v113, v112
	global_atomic_add_f32 v[114:115], v112, off
; __device__ __forceinline__ unsigned pk2(float lo, float hi) { f32x2_t v = {lo, hi}; bf16x2_t b = __builtin_convertvector(v, bf16x2_t); return __builtin_bit_cast(unsigned, b); }
; __device__ __forceinline__ float xor16_sum(float v) { float a = v, b = v; swap16(a, b); return a + b; }
; __device__ __forceinline__ float xor32_sum(float v) { float a = v, b = v; swap32(a, b); return a + b; }
;     __device__ __forceinline__ void operator()(const f32x4 (&acc)[2][2][4][2], const Unit& u, int wr, int wc, int fr, int fq) const {
;     ...
;                 const int row = row0 + ai * HALF + m * 16; float sq = 0.f;
; #pragma unroll
;                 for (int bj = 0; bj < 2; ++bj)
; #pragma unroll
;                     for (int n = 0; n < 2; ++n) {
;                         const size_t idx = (size_t)row * ldc + u.pn * BM + bj * HALF + wc * 32 + 8 * fq + 4 * n;
;                         const f32x4 b = *(const f32x4*)(base + idx);
;                         const f32x4 v = b + acc[ai][bj][m][n] * alpha;
;                         *(f32x4*)(out + idx) = v;
;                         if (NORM) { u32x2 w; w.x = pk2(v[0], v[1]); w.y = pk2(v[2], v[3]); *(u32x2*)(xb + idx) = w; sq += (v[0] * v[0] + v[1] * v[1]) + (v[2] * v[2] + v[3] * v[3]); }
;                     }
;                 if (NORM) { sq = xor16_sum(sq); sq = xor32_sum(sq); if (fq == 0) __hip_atomic_fetch_add(ss + row, sq, __ATOMIC_RELAXED, __HIP_MEMORY_SCOPE_AGENT); }
.LBB0_1210:
	s_or_b64 exec, exec, s[12:13]
	v_or_b32_e32 v112, 16, v148
	v_ashrrev_i32_e32 v113, 31, v112
	v_lshlrev_b64 v[114:115], 11, v[112:113]
	v_lshl_add_u64 v[118:119], v[114:115], 0, v[146:147]
	v_lshl_add_u64 v[120:121], v[118:119], 2, s[30:31]
	s_nop 0
	v_lshlrev_b64 v[118:119], 1, v[118:119]
	v_lshl_add_u64 v[122:123], s[6:7], 0, v[118:119]
	s_nop 0
	s_waitcnt vmcnt(20)
	v_pk_add_f32 v[110:111], v[110:111], v[182:183]
	v_pk_add_f32 v[108:109], v[108:109], v[180:181]
	v_cvt_pk_bf16_f32 v115, v110, v111
	v_cvt_pk_bf16_f32 v114, v108, v109
	global_store_dwordx4 v[120:121], v[108:111], off
	global_store_dwordx2 v[122:123], v[114:115], off
	s_nop 0
	v_or_b32_e32 v122, 8, v118
	v_mov_b32_e32 v123, v119
	v_lshl_add_u64 v[122:123], s[6:7], 0, v[122:123]
	v_mul_f32_e32 v109, v109, v109
	v_mul_f32_e32 v111, v111, v111
	v_fmac_f32_e32 v109, v108, v108
	v_fmac_f32_e32 v111, v110, v110
	v_add_f32_e32 v108, v109, v111
	s_nop 0
	v_pk_add_f32 v[106:107], v[106:107], v[190:191]
	v_pk_add_f32 v[104:105], v[104:105], v[188:189]
	v_cvt_pk_bf16_f32 v115, v106, v107
	v_cvt_pk_bf16_f32 v114, v104, v105
	global_store_dwordx4 v[120:121], v[104:107], off offset:16
	global_store_dwordx2 v[122:123], v[114:115], off
	s_nop 0
	v_or_b32_e32 v122, 0x100, v118
	v_mov_b32_e32 v123, v119
	v_lshl_add_u64 v[122:123], s[6:7], 0, v[122:123]
	v_mul_f32_e32 v105, v105, v105
	v_mul_f32_e32 v107, v107, v107
	v_fmac_f32_e32 v105, v104, v104
	v_fmac_f32_e32 v107, v106, v106
	v_add_f32_e32 v104, v105, v107
	v_add_f32_e32 v104, v108, v104
	v_or_b32_e32 v118, 0x108, v118
	v_lshl_add_u64 v[118:119], s[6:7], 0, v[118:119]
	s_nop 0
	v_pk_add_f32 v[102:103], v[102:103], v[194:195]
	v_pk_add_f32 v[100:101], v[100:101], v[192:193]
	v_cvt_pk_bf16_f32 v115, v102, v103
	v_cvt_pk_bf16_f32 v114, v100, v101
	global_store_dwordx4 v[120:121], v[100:103], off offset:512
	global_store_dwordx2 v[122:123], v[114:115], off
	s_nop 0
	v_mul_f32_e32 v101, v101, v101
	v_mul_f32_e32 v103, v103, v103
	v_fmac_f32_e32 v101, v100, v100
	v_fmac_f32_e32 v103, v102, v102
	v_add_f32_e32 v100, v101, v103
	v_add_f32_e32 v102, v104, v100
	s_nop 0
	v_pk_add_f32 v[98:99], v[98:99], v[198:199]
	v_pk_add_f32 v[96:97], v[96:97], v[196:197]
	v_mov_b32_e32 v230, 0x120000
	v_lshl_add_u64 v[228:229], v[232:233], 0, v[230:231]
	global_load_dwordx4 v[180:183], v[228:229], off nt
	global_load_dwordx4 v[188:191], v[228:229], off offset:16 nt
	global_load_dwordx4 v[192:195], v[228:229], off offset:512 nt
	global_load_dwordx4 v[196:199], v[228:229], off offset:528 nt
	global_store_dwordx4 v[120:121], v[96:99], off offset:528
	v_cvt_pk_bf16_f32 v100, v96, v97
	v_cvt_pk_bf16_f32 v101, v98, v99
	v_mul_f32_e32 v97, v97, v97
	v_mul_f32_e32 v99, v99, v99
	v_fmac_f32_e32 v97, v96, v96
	v_fmac_f32_e32 v99, v98, v98
	v_add_f32_e32 v96, v97, v99
	v_add_f32_e32 v96, v102, v96
	v_mov_b32_e32 v97, v96
	s_nop 1
	v_permlane16_swap_b32 v96, v97
	global_store_dwordx2 v[118:119], v[100:101], off
	v_add_f32_e32 v96, v96, v97
	v_mov_b32_e32 v97, v96
	s_nop 1
	v_permlane32_swap_b32 v96, v97
	s_and_saveexec_b64 s[12:13], s[2:3]
	s_cbranch_execz .LBB0_1212
	v_lshl_add_u64 v[98:99], v[112:113], 2, s[8:9]
	v_add_f32_e32 v96, v96, v97
	global_atomic_add_f32 v[98:99], v96, off
; __device__ __forceinline__ unsigned pk2(float lo, float hi) { f32x2_t v = {lo, hi}; bf16x2_t b = __builtin_convertvector(v, bf16x2_t); return __builtin_bit_cast(unsigned, b); }
; __device__ __forceinline__ float xor16_sum(float v) { float a = v, b = v; swap16(a, b); return a + b; }
; __device__ __forceinline__ float xor32_sum(float v) { float a = v, b = v; swap32(a, b); return a + b; }
;     __device__ __forceinline__ void operator()(const f32x4 (&acc)[2][2][4][2], const Unit& u, int wr, int wc, int fr, int fq) const {
;     ...
;                 const int row = row0 + ai * HALF + m * 16; float sq = 0.f;
; #pragma unroll
;                 for (int bj = 0; bj < 2; ++bj)
; #pragma unroll
;                     for (int n = 0; n < 2; ++n) {
;                         const size_t idx = (size_t)row * ldc + u.pn * BM + bj * HALF + wc * 32 + 8 * fq + 4 * n;
;                         const f32x4 b = *(const f32x4*)(base + idx);
;                         const f32x4 v = b + acc[ai][bj][m][n] * alpha;
;                         *(f32x4*)(out + idx) = v;
;                         if (NORM) { u32x2 w; w.x = pk2(v[0], v[1]); w.y = pk2(v[2], v[3]); *(u32x2*)(xb + idx) = w; sq += (v[0] * v[0] + v[1] * v[1]) + (v[2] * v[2] + v[3] * v[3]); }
;                     }
;                 if (NORM) { sq = xor16_sum(sq); sq = xor32_sum(sq); if (fq == 0) __hip_atomic_fetch_add(ss + row, sq, __ATOMIC_RELAXED, __HIP_MEMORY_SCOPE_AGENT); }
.LBB0_1212:
	s_or_b64 exec, exec, s[12:13]
	v_or_b32_e32 v96, 32, v148
	v_ashrrev_i32_e32 v97, 31, v96
	v_lshlrev_b64 v[98:99], 11, v[96:97]
	v_lshl_add_u64 v[102:103], v[98:99], 0, v[146:147]
	v_lshl_add_u64 v[104:105], v[102:103], 2, s[30:31]
	s_nop 0
	v_lshlrev_b64 v[102:103], 1, v[102:103]
	v_lshl_add_u64 v[106:107], s[6:7], 0, v[102:103]
	s_nop 0
	s_waitcnt vmcnt(28)
	v_pk_add_f32 v[94:95], v[94:95], v[202:203]
	v_pk_add_f32 v[92:93], v[92:93], v[200:201]
	v_cvt_pk_bf16_f32 v99, v94, v95
	v_cvt_pk_bf16_f32 v98, v92, v93
	global_store_dwordx4 v[104:105], v[92:95], off
	global_store_dwordx2 v[106:107], v[98:99], off
	s_nop 0
	v_or_b32_e32 v106, 8, v102
	v_mov_b32_e32 v107, v103
	v_lshl_add_u64 v[106:107], s[6:7], 0, v[106:107]
	v_mul_f32_e32 v93, v93, v93
	v_mul_f32_e32 v95, v95, v95
	v_fmac_f32_e32 v93, v92, v92
	v_fmac_f32_e32 v95, v94, v94
	v_add_f32_e32 v92, v93, v95
	s_nop 0
	v_pk_add_f32 v[90:91], v[90:91], v[206:207]
	v_pk_add_f32 v[88:89], v[88:89], v[204:205]
	v_cvt_pk_bf16_f32 v99, v90, v91
	v_cvt_pk_bf16_f32 v98, v88, v89
	global_store_dwordx4 v[104:105], v[88:91], off offset:16
	global_store_dwordx2 v[106:107], v[98:99], off
	s_nop 0
	v_or_b32_e32 v106, 0x100, v102
	v_mov_b32_e32 v107, v103
	v_lshl_add_u64 v[106:107], s[6:7], 0, v[106:107]
	v_mul_f32_e32 v89, v89, v89
	v_mul_f32_e32 v91, v91, v91
	v_fmac_f32_e32 v89, v88, v88
	v_fmac_f32_e32 v91, v90, v90
	v_add_f32_e32 v88, v89, v91
	v_add_f32_e32 v88, v92, v88
	v_or_b32_e32 v102, 0x108, v102
	v_lshl_add_u64 v[102:103], s[6:7], 0, v[102:103]
	s_nop 0
	v_pk_add_f32 v[86:87], v[86:87], v[210:211]
	v_pk_add_f32 v[84:85], v[84:85], v[208:209]
	v_cvt_pk_bf16_f32 v99, v86, v87
	v_cvt_pk_bf16_f32 v98, v84, v85
	global_store_dwordx4 v[104:105], v[84:87], off offset:512
	global_store_dwordx2 v[106:107], v[98:99], off
	s_nop 0
	v_mul_f32_e32 v85, v85, v85
	v_mul_f32_e32 v87, v87, v87
	v_fmac_f32_e32 v85, v84, v84
	v_fmac_f32_e32 v87, v86, v86
	v_add_f32_e32 v84, v85, v87
	v_add_f32_e32 v86, v88, v84
	s_nop 0
	v_pk_add_f32 v[82:83], v[82:83], v[214:215]
	v_pk_add_f32 v[80:81], v[80:81], v[212:213]
	v_mov_b32_e32 v230, 0x140000
	v_lshl_add_u64 v[228:229], v[232:233], 0, v[230:231]
	global_load_dwordx4 v[200:203], v[228:229], off nt
	global_load_dwordx4 v[204:207], v[228:229], off offset:16 nt
	global_load_dwordx4 v[208:211], v[228:229], off offset:512 nt
	global_load_dwordx4 v[212:215], v[228:229], off offset:528 nt
	global_store_dwordx4 v[104:105], v[80:83], off offset:528
	v_cvt_pk_bf16_f32 v84, v80, v81
	v_cvt_pk_bf16_f32 v85, v82, v83
	v_mul_f32_e32 v81, v81, v81
	v_mul_f32_e32 v83, v83, v83
	v_fmac_f32_e32 v81, v80, v80
	v_fmac_f32_e32 v83, v82, v82
	v_add_f32_e32 v80, v81, v83
	v_add_f32_e32 v80, v86, v80
	v_mov_b32_e32 v81, v80
	s_nop 1
	v_permlane16_swap_b32 v80, v81
	global_store_dwordx2 v[102:103], v[84:85], off
	v_add_f32_e32 v80, v80, v81
	v_mov_b32_e32 v81, v80
	s_nop 1
	v_permlane32_swap_b32 v80, v81
	s_and_saveexec_b64 s[12:13], s[2:3]
	s_cbranch_execz .LBB0_1214
	v_lshl_add_u64 v[82:83], v[96:97], 2, s[8:9]
	v_add_f32_e32 v80, v80, v81
	global_atomic_add_f32 v[82:83], v80, off
.LBB0_1214:
	s_or_b64 exec, exec, s[12:13]
	v_or_b32_e32 v80, 48, v148
	v_ashrrev_i32_e32 v81, 31, v80
	v_lshlrev_b64 v[82:83], 11, v[80:81]
	v_lshl_add_u64 v[86:87], v[82:83], 0, v[146:147]
	v_lshl_add_u64 v[88:89], v[86:87], 2, s[30:31]
	s_nop 0
	v_lshlrev_b64 v[86:87], 1, v[86:87]
	v_lshl_add_u64 v[90:91], s[6:7], 0, v[86:87]
	s_nop 0
	s_waitcnt vmcnt(36)
	v_pk_add_f32 v[78:79], v[78:79], v[218:219]
	v_pk_add_f32 v[76:77], v[76:77], v[216:217]
	v_cvt_pk_bf16_f32 v83, v78, v79
	v_cvt_pk_bf16_f32 v82, v76, v77
	global_store_dwordx4 v[88:89], v[76:79], off
	global_store_dwordx2 v[90:91], v[82:83], off
	s_nop 0
	v_or_b32_e32 v90, 8, v86
	v_mov_b32_e32 v91, v87
	v_lshl_add_u64 v[90:91], s[6:7], 0, v[90:91]
	v_mul_f32_e32 v77, v77, v77
	v_mul_f32_e32 v79, v79, v79
	v_fmac_f32_e32 v77, v76, v76
	v_fmac_f32_e32 v79, v78, v78
	v_add_f32_e32 v76, v77, v79
	s_nop 0
	v_pk_add_f32 v[74:75], v[74:75], v[222:223]
	v_pk_add_f32 v[72:73], v[72:73], v[220:221]
	v_cvt_pk_bf16_f32 v83, v74, v75
	v_cvt_pk_bf16_f32 v82, v72, v73
	global_store_dwordx4 v[88:89], v[72:75], off offset:16
	global_store_dwordx2 v[90:91], v[82:83], off
	s_nop 0
	v_or_b32_e32 v90, 0x100, v86
	v_mov_b32_e32 v91, v87
	v_lshl_add_u64 v[90:91], s[6:7], 0, v[90:91]
	v_mul_f32_e32 v73, v73, v73
	v_mul_f32_e32 v75, v75, v75
	v_fmac_f32_e32 v73, v72, v72
	v_fmac_f32_e32 v75, v74, v74
	v_add_f32_e32 v72, v73, v75
	v_add_f32_e32 v72, v76, v72
	v_or_b32_e32 v86, 0x108, v86
	v_lshl_add_u64 v[86:87], s[6:7], 0, v[86:87]
	s_nop 0
	v_pk_add_f32 v[70:71], v[70:71], v[226:227]
	v_pk_add_f32 v[68:69], v[68:69], v[224:225]
	v_cvt_pk_bf16_f32 v83, v70, v71
	v_cvt_pk_bf16_f32 v82, v68, v69
	global_store_dwordx4 v[88:89], v[68:71], off offset:512
	global_store_dwordx2 v[90:91], v[82:83], off
	s_nop 0
	v_mul_f32_e32 v69, v69, v69
	v_mul_f32_e32 v71, v71, v71
	v_fmac_f32_e32 v69, v68, v68
	v_fmac_f32_e32 v71, v70, v70
	v_add_f32_e32 v68, v69, v71
	v_add_f32_e32 v70, v72, v68
	s_nop 0
	v_pk_add_f32 v[66:67], v[66:67], v[236:237]
	v_pk_add_f32 v[64:65], v[64:65], v[234:235]
	v_mov_b32_e32 v230, 0x160000
	v_lshl_add_u64 v[228:229], v[232:233], 0, v[230:231]
	global_load_dwordx4 v[216:219], v[228:229], off nt
	global_load_dwordx4 v[220:223], v[228:229], off offset:16 nt
	global_load_dwordx4 v[224:227], v[228:229], off offset:512 nt
	global_load_dwordx4 v[234:237], v[228:229], off offset:528 nt
	global_store_dwordx4 v[88:89], v[64:67], off offset:528
	v_cvt_pk_bf16_f32 v68, v64, v65
	v_cvt_pk_bf16_f32 v69, v66, v67
	v_mul_f32_e32 v65, v65, v65
	v_mul_f32_e32 v67, v67, v67
	v_fmac_f32_e32 v65, v64, v64
	v_fmac_f32_e32 v67, v66, v66
	v_add_f32_e32 v64, v65, v67
	v_add_f32_e32 v64, v70, v64
	v_mov_b32_e32 v65, v64
	s_nop 1
	v_permlane16_swap_b32 v64, v65
	global_store_dwordx2 v[86:87], v[68:69], off
	v_add_f32_e32 v64, v64, v65
	v_mov_b32_e32 v65, v64
	s_nop 1
	v_permlane32_swap_b32 v64, v65
	s_and_saveexec_b64 s[12:13], s[2:3]
	s_cbranch_execz .LBB0_1216
	v_lshl_add_u64 v[66:67], v[80:81], 2, s[8:9]
	v_add_f32_e32 v64, v64, v65
	global_atomic_add_f32 v[66:67], v64, off

; __device__ __forceinline__ unsigned pk2(float lo, float hi) { f32x2_t v = {lo, hi}; bf16x2_t b = __builtin_convertvector(v, bf16x2_t); return __builtin_bit_cast(unsigned, b); }
; __device__ __forceinline__ float xor16_sum(float v) { float a = v, b = v; swap16(a, b); return a + b; }
; __device__ __forceinline__ float xor32_sum(float v) { float a = v, b = v; swap32(a, b); return a + b; }
;     __device__ __forceinline__ void operator()(const f32x4 (&acc)[2][2][4][2], const Unit& u, int wr, int wc, int fr, int fq) const {
;     ...
;                 const int row = row0 + ai * HALF + m * 16; float sq = 0.f;
; #pragma unroll
;                 for (int bj = 0; bj < 2; ++bj)
; #pragma unroll
;                     for (int n = 0; n < 2; ++n) {
;                         const size_t idx = (size_t)row * ldc + u.pn * BM + bj * HALF + wc * 32 + 8 * fq + 4 * n;
;                         const f32x4 b = *(const f32x4*)(base + idx);
;                         const f32x4 v = b + acc[ai][bj][m][n] * alpha;
;                         *(f32x4*)(out + idx) = v;
;                         if (NORM) { u32x2 w; w.x = pk2(v[0], v[1]); w.y = pk2(v[2], v[3]); *(u32x2*)(xb + idx) = w; sq += (v[0] * v[0] + v[1] * v[1]) + (v[2] * v[2] + v[3] * v[3]); }
;                     }
;                 if (NORM) { sq = xor16_sum(sq); sq = xor32_sum(sq); if (fq == 0) __hip_atomic_fetch_add(ss + row, sq, __ATOMIC_RELAXED, __HIP_MEMORY_SCOPE_AGENT); }
.LBB0_1605:
	v_lshl_add_u32 v148, s12, 8, v137
	s_lshl_b32 s12, s28, 8
	s_ashr_i32 s13, s12, 31
	v_ashrrev_i32_e32 v149, 31, v148
	v_mov_b32_e32 v147, s13
	v_or_b32_e32 v146, s12, v136
	v_lshlrev_b64 v[154:155], 11, v[148:149]
	v_lshl_add_u64 v[158:159], v[154:155], 0, v[146:147]
	v_lshl_add_u64 v[160:161], v[158:159], 2, s[30:31]
	v_mov_b32_e32 v232, v160
	v_mov_b32_e32 v233, v161
	v_mov_b32_e32 v231, 0
	v_mov_b32_e32 v230, 0x0
	v_lshl_add_u64 v[228:229], v[232:233], 0, v[230:231]
	global_load_dwordx4 v[164:167], v[228:229], off nt
	global_load_dwordx4 v[168:171], v[228:229], off offset:16 nt
	global_load_dwordx4 v[172:175], v[228:229], off offset:512 nt
	global_load_dwordx4 v[176:179], v[228:229], off offset:528 nt
	v_mov_b32_e32 v230, 0x20000
	v_lshl_add_u64 v[228:229], v[232:233], 0, v[230:231]
	global_load_dwordx4 v[180:183], v[228:229], off nt
	global_load_dwordx4 v[188:191], v[228:229], off offset:16 nt
	global_load_dwordx4 v[192:195], v[228:229], off offset:512 nt
	global_load_dwordx4 v[196:199], v[228:229], off offset:528 nt
	v_mov_b32_e32 v230, 0x40000
	v_lshl_add_u64 v[228:229], v[232:233], 0, v[230:231]
	global_load_dwordx4 v[200:203], v[228:229], off nt
	global_load_dwordx4 v[204:207], v[228:229], off offset:16 nt
	global_load_dwordx4 v[208:211], v[228:229], off offset:512 nt
	global_load_dwordx4 v[212:215], v[228:229], off offset:528 nt
	v_mov_b32_e32 v230, 0x60000
	v_lshl_add_u64 v[228:229], v[232:233], 0, v[230:231]
	global_load_dwordx4 v[216:219], v[228:229], off nt
	global_load_dwordx4 v[220:223], v[228:229], off offset:16 nt
	global_load_dwordx4 v[224:227], v[228:229], off offset:512 nt
	global_load_dwordx4 v[234:237], v[228:229], off offset:528 nt
	s_nop 0
	v_lshlrev_b64 v[158:159], 1, v[158:159]
	v_lshl_add_u64 v[162:163], s[40:41], 0, v[158:159]
	s_nop 0
	s_waitcnt vmcnt(12)
	v_pk_add_f32 v[126:127], v[126:127], v[166:167]
	v_pk_add_f32 v[124:125], v[124:125], v[164:165]
	v_cvt_pk_bf16_f32 v155, v126, v127
	v_cvt_pk_bf16_f32 v154, v124, v125
	global_store_dwordx4 v[160:161], v[124:127], off
	global_store_dwordx2 v[162:163], v[154:155], off
	s_nop 0
	v_or_b32_e32 v162, 8, v158
	v_mov_b32_e32 v163, v159
	v_lshl_add_u64 v[162:163], s[40:41], 0, v[162:163]
	v_mul_f32_e32 v125, v125, v125
	v_mul_f32_e32 v127, v127, v127
	v_fmac_f32_e32 v125, v124, v124
	v_fmac_f32_e32 v127, v126, v126
	v_add_f32_e32 v124, v125, v127
	s_nop 0
	v_pk_add_f32 v[122:123], v[122:123], v[170:171]
	v_pk_add_f32 v[120:121], v[120:121], v[168:169]
	v_cvt_pk_bf16_f32 v155, v122, v123
	v_cvt_pk_bf16_f32 v154, v120, v121
	global_store_dwordx4 v[160:161], v[120:123], off offset:16
	global_store_dwordx2 v[162:163], v[154:155], off
	s_nop 0
	v_or_b32_e32 v162, 0x100, v158
	v_mov_b32_e32 v163, v159
	v_lshl_add_u64 v[162:163], s[40:41], 0, v[162:163]
	v_mul_f32_e32 v121, v121, v121
	v_mul_f32_e32 v123, v123, v123
	v_fmac_f32_e32 v121, v120, v120
	v_fmac_f32_e32 v123, v122, v122
	v_add_f32_e32 v120, v121, v123
	v_add_f32_e32 v120, v124, v120
	v_or_b32_e32 v158, 0x108, v158
	v_lshl_add_u64 v[158:159], s[40:41], 0, v[158:159]
	s_nop 0
	v_pk_add_f32 v[118:119], v[118:119], v[174:175]
	v_pk_add_f32 v[116:117], v[116:117], v[172:173]
	v_cvt_pk_bf16_f32 v155, v118, v119
	v_cvt_pk_bf16_f32 v154, v116, v117
	global_store_dwordx4 v[160:161], v[116:119], off offset:512
	global_store_dwordx2 v[162:163], v[154:155], off
	s_nop 0
	v_mul_f32_e32 v117, v117, v117
	v_mul_f32_e32 v119, v119, v119
	v_fmac_f32_e32 v117, v116, v116
	v_fmac_f32_e32 v119, v118, v118
	v_add_f32_e32 v116, v117, v119
	v_add_f32_e32 v118, v120, v116
	s_nop 0
	v_pk_add_f32 v[114:115], v[114:115], v[178:179]
	v_pk_add_f32 v[112:113], v[112:113], v[176:177]
	v_mov_b32_e32 v230, 0x100000
	v_lshl_add_u64 v[228:229], v[232:233], 0, v[230:231]
	global_load_dwordx4 v[164:167], v[228:229], off nt
	global_load_dwordx4 v[168:171], v[228:229], off offset:16 nt
	global_load_dwordx4 v[172:175], v[228:229], off offset:512 nt
	global_load_dwordx4 v[176:179], v[228:229], off offset:528 nt
	global_store_dwordx4 v[160:161], v[112:115], off offset:528
	v_cvt_pk_bf16_f32 v116, v112, v113
	v_cvt_pk_bf16_f32 v117, v114, v115
	v_mul_f32_e32 v113, v113, v113
	v_mul_f32_e32 v115, v115, v115
	v_fmac_f32_e32 v113, v112, v112
	v_fmac_f32_e32 v115, v114, v114
	v_add_f32_e32 v112, v113, v115
	v_add_f32_e32 v112, v118, v112
	v_mov_b32_e32 v113, v112
	s_nop 1
	v_permlane16_swap_b32 v113, v112
	global_store_dwordx2 v[158:159], v[116:117], off
	v_add_f32_e32 v112, v113, v112
	v_mov_b32_e32 v113, v112
	s_nop 1
	v_permlane32_swap_b32 v113, v112
	s_and_saveexec_b64 s[12:13], s[2:3]
	s_cbranch_execz .LBB0_1607
	v_lshl_add_u64 v[114:115], v[148:149], 2, s[6:7]
	v_add_f32_e32 v112, v113, v112
	global_atomic_add_f32 v[114:115], v112, off
; __device__ __forceinline__ unsigned pk2(float lo, float hi) { f32x2_t v = {lo, hi}; bf16x2_t b = __builtin_convertvector(v, bf16x2_t); return __builtin_bit_cast(unsigned, b); }
; __device__ __forceinline__ float xor16_sum(float v) { float a = v, b = v; swap16(a, b); return a + b; }
; __device__ __forceinline__ float xor32_sum(float v) { float a = v, b = v; swap32(a, b); return a + b; }
;     __device__ __forceinline__ void operator()(const f32x4 (&acc)[2][2][4][2], const Unit& u, int wr, int wc, int fr, int fq) const {
;     ...
;                 const int row = row0 + ai * HALF + m * 16; float sq = 0.f;
; #pragma unroll
;                 for (int bj = 0; bj < 2; ++bj)
; #pragma unroll
;                     for (int n = 0; n < 2; ++n) {
;                         const size_t idx = (size_t)row * ldc + u.pn * BM + bj * HALF + wc * 32 + 8 * fq + 4 * n;
;                         const f32x4 b = *(const f32x4*)(base + idx);
;                         const f32x4 v = b + acc[ai][bj][m][n] * alpha;
;                         *(f32x4*)(out + idx) = v;
;                         if (NORM) { u32x2 w; w.x = pk2(v[0], v[1]); w.y = pk2(v[2], v[3]); *(u32x2*)(xb + idx) = w; sq += (v[0] * v[0] + v[1] * v[1]) + (v[2] * v[2] + v[3] * v[3]); }
;                     }
;                 if (NORM) { sq = xor16_sum(sq); sq = xor32_sum(sq); if (fq == 0) __hip_atomic_fetch_add(ss + row, sq, __ATOMIC_RELAXED, __HIP_MEMORY_SCOPE_AGENT); }
.LBB0_1607:
	s_or_b64 exec, exec, s[12:13]
	v_or_b32_e32 v112, 16, v148
	v_ashrrev_i32_e32 v113, 31, v112
	v_lshlrev_b64 v[114:115], 11, v[112:113]
	v_lshl_add_u64 v[118:119], v[114:115], 0, v[146:147]
	v_lshl_add_u64 v[120:121], v[118:119], 2, s[30:31]
	s_nop 0
	v_lshlrev_b64 v[118:119], 1, v[118:119]
	v_lshl_add_u64 v[122:123], s[40:41], 0, v[118:119]
	s_nop 0
	s_waitcnt vmcnt(20)
	v_pk_add_f32 v[110:111], v[110:111], v[182:183]
	v_pk_add_f32 v[108:109], v[108:109], v[180:181]
	v_cvt_pk_bf16_f32 v115, v110, v111
	v_cvt_pk_bf16_f32 v114, v108, v109
	global_store_dwordx4 v[120:121], v[108:111], off
	global_store_dwordx2 v[122:123], v[114:115], off
	s_nop 0
	v_or_b32_e32 v122, 8, v118
	v_mov_b32_e32 v123, v119
	v_lshl_add_u64 v[122:123], s[40:41], 0, v[122:123]
	v_mul_f32_e32 v109, v109, v109
	v_mul_f32_e32 v111, v111, v111
	v_fmac_f32_e32 v109, v108, v108
	v_fmac_f32_e32 v111, v110, v110
	v_add_f32_e32 v108, v109, v111
	s_nop 0
	v_pk_add_f32 v[106:107], v[106:107], v[190:191]
	v_pk_add_f32 v[104:105], v[104:105], v[188:189]
	v_cvt_pk_bf16_f32 v115, v106, v107
	v_cvt_pk_bf16_f32 v114, v104, v105
	global_store_dwordx4 v[120:121], v[104:107], off offset:16
	global_store_dwordx2 v[122:123], v[114:115], off
	s_nop 0
	v_or_b32_e32 v122, 0x100, v118
	v_mov_b32_e32 v123, v119
	v_lshl_add_u64 v[122:123], s[40:41], 0, v[122:123]
	v_mul_f32_e32 v105, v105, v105
	v_mul_f32_e32 v107, v107, v107
	v_fmac_f32_e32 v105, v104, v104
	v_fmac_f32_e32 v107, v106, v106
	v_add_f32_e32 v104, v105, v107
	v_add_f32_e32 v104, v108, v104
	v_or_b32_e32 v118, 0x108, v118
	v_lshl_add_u64 v[118:119], s[40:41], 0, v[118:119]
	s_nop 0
	v_pk_add_f32 v[102:103], v[102:103], v[194:195]
	v_pk_add_f32 v[100:101], v[100:101], v[192:193]
	v_cvt_pk_bf16_f32 v115, v102, v103
	v_cvt_pk_bf16_f32 v114, v100, v101
	global_store_dwordx4 v[120:121], v[100:103], off offset:512
	global_store_dwordx2 v[122:123], v[114:115], off
	s_nop 0
	v_mul_f32_e32 v101, v101, v101
	v_mul_f32_e32 v103, v103, v103
	v_fmac_f32_e32 v101, v100, v100
	v_fmac_f32_e32 v103, v102, v102
	v_add_f32_e32 v100, v101, v103
	v_add_f32_e32 v102, v104, v100
	s_nop 0
	v_pk_add_f32 v[98:99], v[98:99], v[198:199]
	v_pk_add_f32 v[96:97], v[96:97], v[196:197]
	v_mov_b32_e32 v230, 0x120000
	v_lshl_add_u64 v[228:229], v[232:233], 0, v[230:231]
	global_load_dwordx4 v[180:183], v[228:229], off nt
	global_load_dwordx4 v[188:191], v[228:229], off offset:16 nt
	global_load_dwordx4 v[192:195], v[228:229], off offset:512 nt
	global_load_dwordx4 v[196:199], v[228:229], off offset:528 nt
	global_store_dwordx4 v[120:121], v[96:99], off offset:528
	v_cvt_pk_bf16_f32 v100, v96, v97
	v_cvt_pk_bf16_f32 v101, v98, v99
	v_mul_f32_e32 v97, v97, v97
	v_mul_f32_e32 v99, v99, v99
	v_fmac_f32_e32 v97, v96, v96
	v_fmac_f32_e32 v99, v98, v98
	v_add_f32_e32 v96, v97, v99
	v_add_f32_e32 v96, v102, v96
	v_mov_b32_e32 v97, v96
	s_nop 1
	v_permlane16_swap_b32 v96, v97
	global_store_dwordx2 v[118:119], v[100:101], off
	v_add_f32_e32 v96, v96, v97
	v_mov_b32_e32 v97, v96
	s_nop 1
	v_permlane32_swap_b32 v96, v97
	s_and_saveexec_b64 s[12:13], s[2:3]
	s_cbranch_execz .LBB0_1609
	v_lshl_add_u64 v[98:99], v[112:113], 2, s[6:7]
	v_add_f32_e32 v96, v96, v97
	global_atomic_add_f32 v[98:99], v96, off
; __device__ __forceinline__ unsigned pk2(float lo, float hi) { f32x2_t v = {lo, hi}; bf16x2_t b = __builtin_convertvector(v, bf16x2_t); return __builtin_bit_cast(unsigned, b); }
; __device__ __forceinline__ float xor16_sum(float v) { float a = v, b = v; swap16(a, b); return a + b; }
; __device__ __forceinline__ float xor32_sum(float v) { float a = v, b = v; swap32(a, b); return a + b; }
;     __device__ __forceinline__ void operator()(const f32x4 (&acc)[2][2][4][2], const Unit& u, int wr, int wc, int fr, int fq) const {
;     ...
;                 const int row = row0 + ai * HALF + m * 16; float sq = 0.f;
; #pragma unroll
;                 for (int bj = 0; bj < 2; ++bj)
; #pragma unroll
;                     for (int n = 0; n < 2; ++n) {
;                         const size_t idx = (size_t)row * ldc + u.pn * BM + bj * HALF + wc * 32 + 8 * fq + 4 * n;
;                         const f32x4 b = *(const f32x4*)(base + idx);
;                         const f32x4 v = b + acc[ai][bj][m][n] * alpha;
;                         *(f32x4*)(out + idx) = v;
;                         if (NORM) { u32x2 w; w.x = pk2(v[0], v[1]); w.y = pk2(v[2], v[3]); *(u32x2*)(xb + idx) = w; sq += (v[0] * v[0] + v[1] * v[1]) + (v[2] * v[2] + v[3] * v[3]); }
;                     }
;                 if (NORM) { sq = xor16_sum(sq); sq = xor32_sum(sq); if (fq == 0) __hip_atomic_fetch_add(ss + row, sq, __ATOMIC_RELAXED, __HIP_MEMORY_SCOPE_AGENT); }
.LBB0_1609:
	s_or_b64 exec, exec, s[12:13]
	v_or_b32_e32 v96, 32, v148
	v_ashrrev_i32_e32 v97, 31, v96
	v_lshlrev_b64 v[98:99], 11, v[96:97]
	v_lshl_add_u64 v[102:103], v[98:99], 0, v[146:147]
	v_lshl_add_u64 v[104:105], v[102:103], 2, s[30:31]
	s_nop 0
	v_lshlrev_b64 v[102:103], 1, v[102:103]
	v_lshl_add_u64 v[106:107], s[40:41], 0, v[102:103]
	s_nop 0
	s_waitcnt vmcnt(28)
	v_pk_add_f32 v[94:95], v[94:95], v[202:203]
	v_pk_add_f32 v[92:93], v[92:93], v[200:201]
	v_cvt_pk_bf16_f32 v99, v94, v95
	v_cvt_pk_bf16_f32 v98, v92, v93
	global_store_dwordx4 v[104:105], v[92:95], off
	global_store_dwordx2 v[106:107], v[98:99], off
	s_nop 0
	v_or_b32_e32 v106, 8, v102
	v_mov_b32_e32 v107, v103
	v_lshl_add_u64 v[106:107], s[40:41], 0, v[106:107]
	v_mul_f32_e32 v93, v93, v93
	v_mul_f32_e32 v95, v95, v95
	v_fmac_f32_e32 v93, v92, v92
	v_fmac_f32_e32 v95, v94, v94
	v_add_f32_e32 v92, v93, v95
	s_nop 0
	v_pk_add_f32 v[90:91], v[90:91], v[206:207]
	v_pk_add_f32 v[88:89], v[88:89], v[204:205]
	v_cvt_pk_bf16_f32 v99, v90, v91
	v_cvt_pk_bf16_f32 v98, v88, v89
	global_store_dwordx4 v[104:105], v[88:91], off offset:16
	global_store_dwordx2 v[106:107], v[98:99], off
	s_nop 0
	v_or_b32_e32 v106, 0x100, v102
	v_mov_b32_e32 v107, v103
	v_lshl_add_u64 v[106:107], s[40:41], 0, v[106:107]
	v_mul_f32_e32 v89, v89, v89
	v_mul_f32_e32 v91, v91, v91
	v_fmac_f32_e32 v89, v88, v88
	v_fmac_f32_e32 v91, v90, v90
	v_add_f32_e32 v88, v89, v91
	v_add_f32_e32 v88, v92, v88
	v_or_b32_e32 v102, 0x108, v102
	v_lshl_add_u64 v[102:103], s[40:41], 0, v[102:103]
	s_nop 0
	v_pk_add_f32 v[86:87], v[86:87], v[210:211]
	v_pk_add_f32 v[84:85], v[84:85], v[208:209]
	v_cvt_pk_bf16_f32 v99, v86, v87
	v_cvt_pk_bf16_f32 v98, v84, v85
	global_store_dwordx4 v[104:105], v[84:87], off offset:512
	global_store_dwordx2 v[106:107], v[98:99], off
	s_nop 0
	v_mul_f32_e32 v85, v85, v85
	v_mul_f32_e32 v87, v87, v87
	v_fmac_f32_e32 v85, v84, v84
	v_fmac_f32_e32 v87, v86, v86
	v_add_f32_e32 v84, v85, v87
	v_add_f32_e32 v86, v88, v84
	s_nop 0
	v_pk_add_f32 v[82:83], v[82:83], v[214:215]
	v_pk_add_f32 v[80:81], v[80:81], v[212:213]
	v_mov_b32_e32 v230, 0x140000
	v_lshl_add_u64 v[228:229], v[232:233], 0, v[230:231]
	global_load_dwordx4 v[200:203], v[228:229], off nt
	global_load_dwordx4 v[204:207], v[228:229], off offset:16 nt
	global_load_dwordx4 v[208:211], v[228:229], off offset:512 nt
	global_load_dwordx4 v[212:215], v[228:229], off offset:528 nt
	global_store_dwordx4 v[104:105], v[80:83], off offset:528
	v_cvt_pk_bf16_f32 v84, v80, v81
	v_cvt_pk_bf16_f32 v85, v82, v83
	v_mul_f32_e32 v81, v81, v81
	v_mul_f32_e32 v83, v83, v83
	v_fmac_f32_e32 v81, v80, v80
	v_fmac_f32_e32 v83, v82, v82
	v_add_f32_e32 v80, v81, v83
	v_add_f32_e32 v80, v86, v80
	v_mov_b32_e32 v81, v80
	s_nop 1
	v_permlane16_swap_b32 v80, v81
	global_store_dwordx2 v[102:103], v[84:85], off
	v_add_f32_e32 v80, v80, v81
	v_mov_b32_e32 v81, v80
	s_nop 1
	v_permlane32_swap_b32 v80, v81
	s_and_saveexec_b64 s[12:13], s[2:3]
	s_cbranch_execz .LBB0_1611
	v_lshl_add_u64 v[82:83], v[96:97], 2, s[6:7]
	v_add_f32_e32 v80, v80, v81
	global_atomic_add_f32 v[82:83], v80, off
.LBB0_1611:
	s_or_b64 exec, exec, s[12:13]
	v_or_b32_e32 v80, 48, v148
	v_ashrrev_i32_e32 v81, 31, v80
	v_lshlrev_b64 v[82:83], 11, v[80:81]
	v_lshl_add_u64 v[86:87], v[82:83], 0, v[146:147]
	v_lshl_add_u64 v[88:89], v[86:87], 2, s[30:31]
	s_nop 0
	v_lshlrev_b64 v[86:87], 1, v[86:87]
	v_lshl_add_u64 v[90:91], s[40:41], 0, v[86:87]
	s_nop 0
	s_waitcnt vmcnt(36)
	v_pk_add_f32 v[78:79], v[78:79], v[218:219]
	v_pk_add_f32 v[76:77], v[76:77], v[216:217]
	v_cvt_pk_bf16_f32 v83, v78, v79
	v_cvt_pk_bf16_f32 v82, v76, v77
	global_store_dwordx4 v[88:89], v[76:79], off
	global_store_dwordx2 v[90:91], v[82:83], off
	s_nop 0
	v_or_b32_e32 v90, 8, v86
	v_mov_b32_e32 v91, v87
	v_lshl_add_u64 v[90:91], s[40:41], 0, v[90:91]
	v_mul_f32_e32 v77, v77, v77
	v_mul_f32_e32 v79, v79, v79
	v_fmac_f32_e32 v77, v76, v76
	v_fmac_f32_e32 v79, v78, v78
	v_add_f32_e32 v76, v77, v79
	s_nop 0
	v_pk_add_f32 v[74:75], v[74:75], v[222:223]
	v_pk_add_f32 v[72:73], v[72:73], v[220:221]
	v_cvt_pk_bf16_f32 v83, v74, v75
	v_cvt_pk_bf16_f32 v82, v72, v73
	global_store_dwordx4 v[88:89], v[72:75], off offset:16
	global_store_dwordx2 v[90:91], v[82:83], off
	s_nop 0
	v_or_b32_e32 v90, 0x100, v86
	v_mov_b32_e32 v91, v87
	v_lshl_add_u64 v[90:91], s[40:41], 0, v[90:91]
	v_mul_f32_e32 v73, v73, v73
	v_mul_f32_e32 v75, v75, v75
	v_fmac_f32_e32 v73, v72, v72
	v_fmac_f32_e32 v75, v74, v74
	v_add_f32_e32 v72, v73, v75
	v_add_f32_e32 v72, v76, v72
	v_or_b32_e32 v86, 0x108, v86
	v_lshl_add_u64 v[86:87], s[40:41], 0, v[86:87]
	s_nop 0
	v_pk_add_f32 v[70:71], v[70:71], v[226:227]
	v_pk_add_f32 v[68:69], v[68:69], v[224:225]
	v_cvt_pk_bf16_f32 v83, v70, v71
	v_cvt_pk_bf16_f32 v82, v68, v69
	global_store_dwordx4 v[88:89], v[68:71], off offset:512
	global_store_dwordx2 v[90:91], v[82:83], off
	s_nop 0
	v_mul_f32_e32 v69, v69, v69
	v_mul_f32_e32 v71, v71, v71
	v_fmac_f32_e32 v69, v68, v68
	v_fmac_f32_e32 v71, v70, v70
	v_add_f32_e32 v68, v69, v71
	v_add_f32_e32 v70, v72, v68
	s_nop 0
	v_pk_add_f32 v[66:67], v[66:67], v[236:237]
	v_pk_add_f32 v[64:65], v[64:65], v[234:235]
	v_mov_b32_e32 v230, 0x160000
	v_lshl_add_u64 v[228:229], v[232:233], 0, v[230:231]
	global_load_dwordx4 v[216:219], v[228:229], off nt
	global_load_dwordx4 v[220:223], v[228:229], off offset:16 nt
	global_load_dwordx4 v[224:227], v[228:229], off offset:512 nt
	global_load_dwordx4 v[234:237], v[228:229], off offset:528 nt
	global_store_dwordx4 v[88:89], v[64:67], off offset:528
	v_cvt_pk_bf16_f32 v68, v64, v65
	v_cvt_pk_bf16_f32 v69, v66, v67
	v_mul_f32_e32 v65, v65, v65
	v_mul_f32_e32 v67, v67, v67
	v_fmac_f32_e32 v65, v64, v64
	v_fmac_f32_e32 v67, v66, v66
	v_add_f32_e32 v64, v65, v67
	v_add_f32_e32 v64, v70, v64
	v_mov_b32_e32 v65, v64
	s_nop 1
	v_permlane16_swap_b32 v64, v65
	global_store_dwordx2 v[86:87], v[68:69], off
	v_add_f32_e32 v64, v64, v65
	v_mov_b32_e32 v65, v64
	s_nop 1
	v_permlane32_swap_b32 v64, v65
	s_and_saveexec_b64 s[12:13], s[2:3]
	s_cbranch_execz .LBB0_1613
	v_lshl_add_u64 v[66:67], v[80:81], 2, s[6:7]
	v_add_f32_e32 v64, v64, v65
	global_atomic_add_f32 v[66:67], v64, off

;     __device__ __forceinline__ void operator()(const f32x4 (&acc)[2][2][4][2], const Unit& u, int wr, int wc, int fr, int fq) const {
;     ...
;                 const int row = row0 + ai * HALF + m * 16; float sq = 0.f;
; #pragma unroll
;                 for (int bj = 0; bj < 2; ++bj)
; #pragma unroll
;                     for (int n = 0; n < 2; ++n) {
;                         const size_t idx = (size_t)row * ldc + u.pn * BM + bj * HALF + wc * 32 + 8 * fq + 4 * n;
;                         const f32x4 b = *(const f32x4*)(base + idx);
;                         const f32x4 v = b + acc[ai][bj][m][n] * alpha;
;                         *(f32x4*)(out + idx) = v;
.LBB0_1775:
	v_lshl_add_u32 v148, s14, 8, v137
	s_lshl_b32 s14, s49, 8
	s_ashr_i32 s24, s14, 31
	v_ashrrev_i32_e32 v149, 31, v148
	v_mov_b32_e32 v147, s24
	v_or_b32_e32 v146, s14, v136
	v_lshlrev_b64 v[150:151], 13, v[148:149]
	v_lshl_add_u64 v[156:157], s[30:31], 0, v[150:151]
	v_lshlrev_b64 v[150:151], 2, v[146:147]
	v_lshl_add_u64 v[146:147], v[156:157], 0, v[150:151]
	v_mov_b32_e32 v232, v146
	v_mov_b32_e32 v233, v147
	v_mov_b32_e32 v231, 0
	v_mov_b32_e32 v230, 0x0
	v_lshl_add_u64 v[228:229], v[232:233], 0, v[230:231]
	global_load_dwordx4 v[164:167], v[228:229], off nt
	global_load_dwordx4 v[168:171], v[228:229], off offset:16 nt
	global_load_dwordx4 v[172:175], v[228:229], off offset:512 nt
	global_load_dwordx4 v[176:179], v[228:229], off offset:528 nt
	v_mov_b32_e32 v230, 0x20000
	v_lshl_add_u64 v[228:229], v[232:233], 0, v[230:231]
	global_load_dwordx4 v[180:183], v[228:229], off nt
	global_load_dwordx4 v[188:191], v[228:229], off offset:16 nt
	global_load_dwordx4 v[192:195], v[228:229], off offset:512 nt
	global_load_dwordx4 v[196:199], v[228:229], off offset:528 nt
	v_mov_b32_e32 v230, 0x40000
	v_lshl_add_u64 v[228:229], v[232:233], 0, v[230:231]
	global_load_dwordx4 v[200:203], v[228:229], off nt
	global_load_dwordx4 v[204:207], v[228:229], off offset:16 nt
	global_load_dwordx4 v[208:211], v[228:229], off offset:512 nt
	global_load_dwordx4 v[212:215], v[228:229], off offset:528 nt
	v_mov_b32_e32 v230, 0x60000
	v_lshl_add_u64 v[228:229], v[232:233], 0, v[230:231]
	global_load_dwordx4 v[216:219], v[228:229], off nt
	global_load_dwordx4 v[220:223], v[228:229], off offset:16 nt
	global_load_dwordx4 v[224:227], v[228:229], off offset:512 nt
	global_load_dwordx4 v[234:237], v[228:229], off offset:528 nt
	s_nop 0
	s_nop 0
	s_mov_b64 s[24:25], -1
	s_nop 0
	s_waitcnt vmcnt(12)
	v_pk_fma_f32 v[122:123], v[122:123], 0.5, v[170:171] op_sel_hi:[1,0,1]
	v_pk_fma_f32 v[126:127], v[126:127], 0.5, v[166:167] op_sel_hi:[1,0,1]
	v_pk_fma_f32 v[124:125], v[124:125], 0.5, v[164:165] op_sel_hi:[1,0,1]
	v_pk_fma_f32 v[120:121], v[120:121], 0.5, v[168:169] op_sel_hi:[1,0,1]
	global_store_dwordx4 v[146:147], v[124:127], off
	global_store_dwordx4 v[146:147], v[120:123], off offset:16
	s_nop 0
	s_nop 0
	s_nop 0
	s_nop 0
	v_pk_fma_f32 v[114:115], v[114:115], 0.5, v[178:179] op_sel_hi:[1,0,1]
	v_pk_fma_f32 v[112:113], v[112:113], 0.5, v[176:177] op_sel_hi:[1,0,1]
	global_store_dwordx4 v[146:147], v[112:115], off offset:528
	s_nop 0
	v_pk_fma_f32 v[118:119], v[118:119], 0.5, v[174:175] op_sel_hi:[1,0,1]
	v_pk_fma_f32 v[116:117], v[116:117], 0.5, v[172:173] op_sel_hi:[1,0,1]
	v_mov_b32_e32 v230, 0x100000
	v_lshl_add_u64 v[228:229], v[232:233], 0, v[230:231]
	global_load_dwordx4 v[164:167], v[228:229], off nt
	global_load_dwordx4 v[168:171], v[228:229], off offset:16 nt
	global_load_dwordx4 v[172:175], v[228:229], off offset:512 nt
	global_load_dwordx4 v[176:179], v[228:229], off offset:528 nt
	v_or_b32_e32 v112, 16, v148
	v_ashrrev_i32_e32 v113, 31, v112
	v_lshlrev_b64 v[112:113], 13, v[112:113]
	v_lshl_add_u64 v[112:113], s[30:31], 0, v[112:113]
	global_store_dwordx4 v[146:147], v[116:119], off offset:512
	v_lshl_add_u64 v[120:121], v[112:113], 0, v[150:151]
	s_nop 0
	s_nop 0
	s_nop 0
	s_waitcnt vmcnt(16)
	v_pk_fma_f32 v[106:107], v[106:107], 0.5, v[190:191] op_sel_hi:[1,0,1]
	s_nop 0
	v_pk_fma_f32 v[110:111], v[110:111], 0.5, v[182:183] op_sel_hi:[1,0,1]
	v_pk_fma_f32 v[108:109], v[108:109], 0.5, v[180:181] op_sel_hi:[1,0,1]
	v_pk_fma_f32 v[104:105], v[104:105], 0.5, v[188:189] op_sel_hi:[1,0,1]
	global_store_dwordx4 v[120:121], v[108:111], off
	global_store_dwordx4 v[120:121], v[104:107], off offset:16
	s_nop 0
	s_nop 0
	s_nop 0
	s_nop 0
	v_pk_fma_f32 v[98:99], v[98:99], 0.5, v[198:199] op_sel_hi:[1,0,1]
	v_pk_fma_f32 v[96:97], v[96:97], 0.5, v[196:197] op_sel_hi:[1,0,1]
	global_store_dwordx4 v[120:121], v[96:99], off offset:528
	s_nop 0
	v_pk_fma_f32 v[102:103], v[102:103], 0.5, v[194:195] op_sel_hi:[1,0,1]
	v_pk_fma_f32 v[100:101], v[100:101], 0.5, v[192:193] op_sel_hi:[1,0,1]
	v_mov_b32_e32 v230, 0x120000
	v_lshl_add_u64 v[228:229], v[232:233], 0, v[230:231]
	global_load_dwordx4 v[180:183], v[228:229], off nt
	global_load_dwordx4 v[188:191], v[228:229], off offset:16 nt
	global_load_dwordx4 v[192:195], v[228:229], off offset:512 nt
	global_load_dwordx4 v[196:199], v[228:229], off offset:528 nt
	v_or_b32_e32 v96, 32, v148
	v_ashrrev_i32_e32 v97, 31, v96
	v_lshlrev_b64 v[96:97], 13, v[96:97]
	v_lshl_add_u64 v[96:97], s[30:31], 0, v[96:97]
	global_store_dwordx4 v[120:121], v[100:103], off offset:512
	v_lshl_add_u64 v[104:105], v[96:97], 0, v[150:151]
	s_nop 0
	s_nop 0
	s_nop 0
	s_waitcnt vmcnt(20)
	v_pk_fma_f32 v[90:91], v[90:91], 0.5, v[206:207] op_sel_hi:[1,0,1]
	s_nop 0
	v_pk_fma_f32 v[94:95], v[94:95], 0.5, v[202:203] op_sel_hi:[1,0,1]
	v_pk_fma_f32 v[92:93], v[92:93], 0.5, v[200:201] op_sel_hi:[1,0,1]
	v_pk_fma_f32 v[88:89], v[88:89], 0.5, v[204:205] op_sel_hi:[1,0,1]
	global_store_dwordx4 v[104:105], v[92:95], off
	global_store_dwordx4 v[104:105], v[88:91], off offset:16
	s_nop 0
	s_nop 0
	s_nop 0
	s_nop 0
	v_pk_fma_f32 v[82:83], v[82:83], 0.5, v[214:215] op_sel_hi:[1,0,1]
	v_pk_fma_f32 v[80:81], v[80:81], 0.5, v[212:213] op_sel_hi:[1,0,1]
	global_store_dwordx4 v[104:105], v[80:83], off offset:528
	s_nop 0
	v_pk_fma_f32 v[86:87], v[86:87], 0.5, v[210:211] op_sel_hi:[1,0,1]
	v_pk_fma_f32 v[84:85], v[84:85], 0.5, v[208:209] op_sel_hi:[1,0,1]
	v_mov_b32_e32 v230, 0x140000
	v_lshl_add_u64 v[228:229], v[232:233], 0, v[230:231]
	global_load_dwordx4 v[200:203], v[228:229], off nt
	global_load_dwordx4 v[204:207], v[228:229], off offset:16 nt
	global_load_dwordx4 v[208:211], v[228:229], off offset:512 nt
	global_load_dwordx4 v[212:215], v[228:229], off offset:528 nt
	v_or_b32_e32 v80, 48, v148
	v_ashrrev_i32_e32 v81, 31, v80
	v_lshlrev_b64 v[80:81], 13, v[80:81]
	v_lshl_add_u64 v[80:81], s[30:31], 0, v[80:81]
	global_store_dwordx4 v[104:105], v[84:87], off offset:512
	v_lshl_add_u64 v[88:89], v[80:81], 0, v[150:151]
	s_nop 0
	s_nop 0
	s_nop 0
	s_waitcnt vmcnt(24)
; #define PG8_BAR __builtin_amdgcn_s_barrier()
;     __device__ __forceinline__ void operator()(const f32x4 (&acc)[2][2][4][2], const Unit& u, int wr, int wc, int fr, int fq) const {
;     ...
;                 const int row = row0 + ai * HALF + m * 16; float sq = 0.f;
; #pragma unroll
;                 for (int bj = 0; bj < 2; ++bj)
; #pragma unroll
;                     for (int n = 0; n < 2; ++n) {
;                         const size_t idx = (size_t)row * ldc + u.pn * BM + bj * HALF + wc * 32 + 8 * fq + 4 * n;
;                         const f32x4 b = *(const f32x4*)(base + idx);
;                         const f32x4 v = b + acc[ai][bj][m][n] * alpha;
;                         *(f32x4*)(out + idx) = v;
; template <class Epi, bool ALIGN_EPI = PG8_ALIGN>
; __device__ __forceinline__ void gemm_phase(LAS unsigned char* lds, const Gemm g, const StaticOrder S, const Epi E) {
;     ...
;         if (ALIGN_EPI) { if (wr == 0) PG8_BAR; }
;         E(acc, cur, wr, wc, fr, fq);
;         if (!has_next) break;
; #pragma unroll
;         for (int a = 0; a < 2; ++a)
; #pragma unroll
;             for (int b = 0; b < 2; ++b)
; #pragma unroll
;                 for (int m = 0; m < 4; ++m)
; #pragma unroll
;                     for (int n = 0; n < 2; ++n) acc[a][b][m][n] = (f32x4){0.f, 0.f, 0.f, 0.f};
;         cur = nxt; cA = nA; cB = nB; ++ui;
;         if (ALIGN_EPI) { if (wr == 1) PG8_BAR; }
	v_pk_fma_f32 v[74:75], v[74:75], 0.5, v[222:223] op_sel_hi:[1,0,1]
	s_nop 0
	v_pk_fma_f32 v[78:79], v[78:79], 0.5, v[218:219] op_sel_hi:[1,0,1]
	v_pk_fma_f32 v[76:77], v[76:77], 0.5, v[216:217] op_sel_hi:[1,0,1]
	v_pk_fma_f32 v[72:73], v[72:73], 0.5, v[220:221] op_sel_hi:[1,0,1]
	global_store_dwordx4 v[88:89], v[76:79], off
	global_store_dwordx4 v[88:89], v[72:75], off offset:16
	s_nop 0
	s_nop 0
	s_nop 0
	s_nop 0
	v_pk_fma_f32 v[66:67], v[66:67], 0.5, v[236:237] op_sel_hi:[1,0,1]
	s_nop 0
	v_pk_fma_f32 v[70:71], v[70:71], 0.5, v[226:227] op_sel_hi:[1,0,1]
	v_pk_fma_f32 v[68:69], v[68:69], 0.5, v[224:225] op_sel_hi:[1,0,1]
	v_pk_fma_f32 v[64:65], v[64:65], 0.5, v[234:235] op_sel_hi:[1,0,1]
	v_mov_b32_e32 v230, 0x160000
	v_lshl_add_u64 v[228:229], v[232:233], 0, v[230:231]
	global_load_dwordx4 v[216:219], v[228:229], off nt
	global_load_dwordx4 v[220:223], v[228:229], off offset:16 nt
	global_load_dwordx4 v[224:227], v[228:229], off offset:512 nt
	global_load_dwordx4 v[234:237], v[228:229], off offset:528 nt
	v_add_co_u32_e32 v74, vcc, s43, v146
	global_store_dwordx4 v[88:89], v[68:71], off offset:512
	global_store_dwordx4 v[88:89], v[64:67], off offset:528
	v_addc_co_u32_e32 v75, vcc, 0, v147, vcc
	v_lshl_add_u64 v[72:73], v[146:147], 0, s[12:13]
	s_nop 0
	s_nop 0
	s_nop 0
	s_waitcnt vmcnt(25)
	v_pk_fma_f32 v[62:63], v[62:63], 0.5, v[166:167] op_sel_hi:[1,0,1]
	v_pk_fma_f32 v[60:61], v[60:61], 0.5, v[164:165] op_sel_hi:[1,0,1]
	s_nop 0
	v_pk_fma_f32 v[58:59], v[58:59], 0.5, v[170:171] op_sel_hi:[1,0,1]
	v_pk_fma_f32 v[56:57], v[56:57], 0.5, v[168:169] op_sel_hi:[1,0,1]
	global_store_dwordx4 v[74:75], v[60:63], off
	global_store_dwordx4 v[72:73], v[56:59], off offset:16
	s_nop 0
	s_nop 0
	s_nop 0
	s_nop 0
	v_pk_fma_f32 v[50:51], v[50:51], 0.5, v[178:179] op_sel_hi:[1,0,1]
	s_nop 0
	v_pk_fma_f32 v[54:55], v[54:55], 0.5, v[174:175] op_sel_hi:[1,0,1]
	v_pk_fma_f32 v[52:53], v[52:53], 0.5, v[172:173] op_sel_hi:[1,0,1]
	v_pk_fma_f32 v[48:49], v[48:49], 0.5, v[176:177] op_sel_hi:[1,0,1]
	v_add_co_u32_e32 v58, vcc, s44, v146
	global_store_dwordx4 v[72:73], v[52:55], off offset:512
	global_store_dwordx4 v[72:73], v[48:51], off offset:528
	v_addc_co_u32_e32 v59, vcc, 0, v147, vcc
	v_lshl_add_u64 v[56:57], v[146:147], 0, s[18:19]
	s_nop 0
	s_nop 0
	s_nop 0
	s_waitcnt vmcnt(21)
	v_pk_fma_f32 v[46:47], v[46:47], 0.5, v[182:183] op_sel_hi:[1,0,1]
	v_pk_fma_f32 v[44:45], v[44:45], 0.5, v[180:181] op_sel_hi:[1,0,1]
	s_nop 0
	v_pk_fma_f32 v[42:43], v[42:43], 0.5, v[190:191] op_sel_hi:[1,0,1]
	v_pk_fma_f32 v[40:41], v[40:41], 0.5, v[188:189] op_sel_hi:[1,0,1]
	global_store_dwordx4 v[58:59], v[44:47], off
	global_store_dwordx4 v[56:57], v[40:43], off offset:16
	s_nop 0
	s_nop 0
	s_nop 0
	s_nop 0
	v_pk_fma_f32 v[34:35], v[34:35], 0.5, v[198:199] op_sel_hi:[1,0,1]
	s_nop 0
	v_pk_fma_f32 v[38:39], v[38:39], 0.5, v[194:195] op_sel_hi:[1,0,1]
	v_pk_fma_f32 v[36:37], v[36:37], 0.5, v[192:193] op_sel_hi:[1,0,1]
	v_pk_fma_f32 v[32:33], v[32:33], 0.5, v[196:197] op_sel_hi:[1,0,1]
	v_add_co_u32_e32 v42, vcc, s45, v146
	global_store_dwordx4 v[56:57], v[36:39], off offset:512
	global_store_dwordx4 v[56:57], v[32:35], off offset:528
	v_addc_co_u32_e32 v43, vcc, 0, v147, vcc
	v_lshl_add_u64 v[40:41], v[146:147], 0, s[20:21]
	s_nop 0
	s_nop 0
	s_nop 0
	s_waitcnt vmcnt(17)
	v_pk_fma_f32 v[30:31], v[30:31], 0.5, v[202:203] op_sel_hi:[1,0,1]
	v_pk_fma_f32 v[28:29], v[28:29], 0.5, v[200:201] op_sel_hi:[1,0,1]
	s_nop 0
	v_pk_fma_f32 v[26:27], v[26:27], 0.5, v[206:207] op_sel_hi:[1,0,1]
	v_pk_fma_f32 v[24:25], v[24:25], 0.5, v[204:205] op_sel_hi:[1,0,1]
	global_store_dwordx4 v[42:43], v[28:31], off
	global_store_dwordx4 v[40:41], v[24:27], off offset:16
	s_nop 0
	s_nop 0
	s_nop 0
	s_nop 0
	v_pk_fma_f32 v[18:19], v[18:19], 0.5, v[214:215] op_sel_hi:[1,0,1]
	s_nop 0
	v_pk_fma_f32 v[22:23], v[22:23], 0.5, v[210:211] op_sel_hi:[1,0,1]
	v_pk_fma_f32 v[20:21], v[20:21], 0.5, v[208:209] op_sel_hi:[1,0,1]
	v_pk_fma_f32 v[16:17], v[16:17], 0.5, v[212:213] op_sel_hi:[1,0,1]
	v_add_co_u32_e32 v26, vcc, s46, v146
	global_store_dwordx4 v[40:41], v[20:23], off offset:512
	global_store_dwordx4 v[40:41], v[16:19], off offset:528
	v_addc_co_u32_e32 v27, vcc, 0, v147, vcc
	s_nop 0
	v_lshl_add_u64 v[16:17], v[146:147], 0, s[4:5]
	s_nop 0
	s_nop 0
	s_and_b64 vcc, exec, s[0:1]
	s_nop 0
	s_waitcnt vmcnt(14)
	v_pk_fma_f32 v[14:15], v[14:15], 0.5, v[218:219] op_sel_hi:[1,0,1]
	v_pk_fma_f32 v[12:13], v[12:13], 0.5, v[216:217] op_sel_hi:[1,0,1]
	s_nop 0
	v_pk_fma_f32 v[10:11], v[10:11], 0.5, v[222:223] op_sel_hi:[1,0,1]
	v_pk_fma_f32 v[8:9], v[8:9], 0.5, v[220:221] op_sel_hi:[1,0,1]
	global_store_dwordx4 v[26:27], v[12:15], off
	global_store_dwordx4 v[16:17], v[8:11], off offset:16
	s_nop 0
	s_nop 0
	s_nop 0
	s_nop 0
	v_pk_fma_f32 v[2:3], v[2:3], 0.5, v[236:237] op_sel_hi:[1,0,1]
	s_nop 0
	v_pk_fma_f32 v[6:7], v[6:7], 0.5, v[226:227] op_sel_hi:[1,0,1]
	v_pk_fma_f32 v[4:5], v[4:5], 0.5, v[224:225] op_sel_hi:[1,0,1]
	v_pk_fma_f32 v[0:1], v[0:1], 0.5, v[234:235] op_sel_hi:[1,0,1]
	global_store_dwordx4 v[16:17], v[4:7], off offset:512
	global_store_dwordx4 v[16:17], v[0:3], off offset:528
	s_cbranch_vccnz .LBB0_1760
	s_andn2_b64 vcc, exec, s[6:7]
	s_cbranch_vccnz .LBB0_1759
	s_barrier
	s_branch .LBB0_1759
